# P0 adaLN modulation on f32-operand MFMA (v_mfma_f32_16x16x4_f32, exact f32 products) instead of 3x bf16 hi/lo split MFMAs: removes split/pack VALU
# speedup vs baseline: 1.0166x; 1.0085x over previous
; __device__ __forceinline__ unsigned f2bf(float f) { unsigned u = __builtin_bit_cast(unsigned, f); return (u + 0x7fffu + ((u >> 16) & 1u)) >> 16; }
; __device__ __forceinline__ f32x4 mfma16(bf16x8 a, bf16x8 b, f32x4 c) { return __builtin_amdgcn_mfma_f32_16x16x32_bf16(a, b, c, 0, 0, 0); }
; #define LDS_WAIT() asm volatile("s_waitcnt lgkmcnt(0)" ::: "memory")
; __device__ __forceinline__ void phase0(const Args& a, LAS unsigned char* lds, int tid, int wave, int lane, int vcu, int G, int pmask) {
;     ...
;             for (int ch = 0; ch < 2; ++ch) {
;                 const int k0 = 128 * wave + 64 * ch;
; #pragma unroll 8
;                 for (int i = 0; i < 32; ++i) { const int kk = 2 * i + (lane >> 5); scr[kk * 33 + (lane & 31)] = wada[(size_t)(k0 + kk) * 6144 + n0 + (lane & 31)]; }
;                 LDS_WAIT(); asm volatile("" ::: "memory");
;     ...
;                         if (b < 129) { const float* cr = b == 0 ? cp + k : cs + (size_t)(b - 1) * DM + k; c0 = *(const f32x4*)cr; c1 = *(const f32x4*)(cr + 4); }
;                         unsigned hb[8], lb[8];
; #pragma unroll
;                         for (int j = 0; j < 8; ++j) { const float c = j < 4 ? c0[j & 3] : c1[j & 3]; const float sv = c * __builtin_amdgcn_rcpf(1.f + __expf(-c)); hb[j] = f2bf(sv); lb[j] = f2bf(sv - __uint_as_float(hb[j] << 16)); }
;                         u32x4 wh, wl; wh.x = hb[0] | (hb[1] << 16); wh.y = hb[2] | (hb[3] << 16); wh.z = hb[4] | (hb[5] << 16); wh.w = hb[6] | (hb[7] << 16);
;                         wl.x = lb[0] | (lb[1] << 16); wl.y = lb[2] | (lb[3] << 16); wl.z = lb[4] | (lb[5] << 16); wl.w = lb[6] | (lb[7] << 16);
;                         const bf16x8 bh = __builtin_bit_cast(bf16x8, wh), bl = __builtin_bit_cast(bf16x8, wl);
; #pragma unroll
;                         for (int nt = 0; nt < 2; ++nt) { acc[nt][bt] = mfma16(ah[nt], bh, acc[nt][bt]); acc[nt][bt] = mfma16(ah[nt], bl, acc[nt][bt]); acc[nt][bt] = mfma16(al[nt], bh, acc[nt][bt]); }
.LBB0_14:
	s_xor_b64 s[54:55], s[56:57], -1
	s_or_b32 s56, s82, s33
	v_or_b32_e32 v75, s56, v1
	v_or_b32_e32 v74, s56, v110
	v_mad_u64_u32 v[76:77], s[86:87], v74, s58, v[144:145]
	v_mad_u32_u24 v78, v110, s59, v116
	s_mov_b64 s[84:85], 0xc000
	global_load_dword v184, v[76:77], off
	v_lshl_add_u64 v[76:77], v[76:77], 0, s[84:85]
	global_load_dword v185, v[76:77], off
	v_lshl_add_u64 v[76:77], v[76:77], 0, s[84:85]
	global_load_dword v186, v[76:77], off
	v_lshl_add_u64 v[76:77], v[76:77], 0, s[84:85]
	global_load_dword v187, v[76:77], off
	v_lshl_add_u64 v[76:77], v[76:77], 0, s[84:85]
	global_load_dword v188, v[76:77], off
	v_lshl_add_u64 v[76:77], v[76:77], 0, s[84:85]
	global_load_dword v189, v[76:77], off
	v_lshl_add_u64 v[76:77], v[76:77], 0, s[84:85]
	global_load_dword v190, v[76:77], off
	v_lshl_add_u64 v[76:77], v[76:77], 0, s[84:85]
	global_load_dword v191, v[76:77], off
	v_lshl_add_u64 v[76:77], v[76:77], 0, s[84:85]
	global_load_dword v192, v[76:77], off
	v_lshl_add_u64 v[76:77], v[76:77], 0, s[84:85]
	global_load_dword v193, v[76:77], off
	v_lshl_add_u64 v[76:77], v[76:77], 0, s[84:85]
	global_load_dword v194, v[76:77], off
	v_lshl_add_u64 v[76:77], v[76:77], 0, s[84:85]
	global_load_dword v195, v[76:77], off
	v_lshl_add_u64 v[76:77], v[76:77], 0, s[84:85]
	global_load_dword v196, v[76:77], off
	v_lshl_add_u64 v[76:77], v[76:77], 0, s[84:85]
	global_load_dword v197, v[76:77], off
	v_lshl_add_u64 v[76:77], v[76:77], 0, s[84:85]
	global_load_dword v198, v[76:77], off
	v_lshl_add_u64 v[76:77], v[76:77], 0, s[84:85]
	global_load_dword v199, v[76:77], off
	v_lshl_add_u64 v[76:77], v[76:77], 0, s[84:85]
	global_load_dword v200, v[76:77], off
	v_lshl_add_u64 v[76:77], v[76:77], 0, s[84:85]
	global_load_dword v201, v[76:77], off
	v_lshl_add_u64 v[76:77], v[76:77], 0, s[84:85]
	global_load_dword v202, v[76:77], off
	v_lshl_add_u64 v[76:77], v[76:77], 0, s[84:85]
	global_load_dword v203, v[76:77], off
	v_lshl_add_u64 v[76:77], v[76:77], 0, s[84:85]
	global_load_dword v204, v[76:77], off
	v_lshl_add_u64 v[76:77], v[76:77], 0, s[84:85]
	global_load_dword v205, v[76:77], off
	v_lshl_add_u64 v[76:77], v[76:77], 0, s[84:85]
	global_load_dword v206, v[76:77], off
	v_lshl_add_u64 v[76:77], v[76:77], 0, s[84:85]
	global_load_dword v207, v[76:77], off
	v_lshl_add_u64 v[76:77], v[76:77], 0, s[84:85]
	global_load_dword v208, v[76:77], off
	v_lshl_add_u64 v[76:77], v[76:77], 0, s[84:85]
	global_load_dword v209, v[76:77], off
	v_lshl_add_u64 v[76:77], v[76:77], 0, s[84:85]
	global_load_dword v210, v[76:77], off
	v_lshl_add_u64 v[76:77], v[76:77], 0, s[84:85]
	global_load_dword v211, v[76:77], off
	v_lshl_add_u64 v[76:77], v[76:77], 0, s[84:85]
	global_load_dword v212, v[76:77], off
	v_lshl_add_u64 v[76:77], v[76:77], 0, s[84:85]
	global_load_dword v213, v[76:77], off
	v_lshl_add_u64 v[76:77], v[76:77], 0, s[84:85]
	global_load_dword v214, v[76:77], off
	v_lshl_add_u64 v[76:77], v[76:77], 0, s[84:85]
	global_load_dword v215, v[76:77], off
	s_waitcnt vmcnt(31)
	ds_write_b32 v78, v184
	s_waitcnt vmcnt(30)
	ds_write_b32 v78, v185 offset:264
	s_waitcnt vmcnt(29)
	ds_write_b32 v78, v186 offset:528
	s_waitcnt vmcnt(28)
	ds_write_b32 v78, v187 offset:792
	s_waitcnt vmcnt(27)
	ds_write_b32 v78, v188 offset:1056
	s_waitcnt vmcnt(26)
	ds_write_b32 v78, v189 offset:1320
	s_waitcnt vmcnt(25)
	ds_write_b32 v78, v190 offset:1584
	s_waitcnt vmcnt(24)
	ds_write_b32 v78, v191 offset:1848
	s_waitcnt vmcnt(23)
	ds_write_b32 v78, v192 offset:2112
	s_waitcnt vmcnt(22)
	ds_write_b32 v78, v193 offset:2376
	s_waitcnt vmcnt(21)
	ds_write_b32 v78, v194 offset:2640
	s_waitcnt vmcnt(20)
	ds_write_b32 v78, v195 offset:2904
	s_waitcnt vmcnt(19)
	ds_write_b32 v78, v196 offset:3168
	s_waitcnt vmcnt(18)
	ds_write_b32 v78, v197 offset:3432
	s_waitcnt vmcnt(17)
	ds_write_b32 v78, v198 offset:3696
	s_waitcnt vmcnt(16)
	ds_write_b32 v78, v199 offset:3960
	s_waitcnt vmcnt(15)
	ds_write_b32 v78, v200 offset:4224
	s_waitcnt vmcnt(14)
	ds_write_b32 v78, v201 offset:4488
	s_waitcnt vmcnt(13)
	ds_write_b32 v78, v202 offset:4752
	s_waitcnt vmcnt(12)
	ds_write_b32 v78, v203 offset:5016
	s_waitcnt vmcnt(11)
	ds_write_b32 v78, v204 offset:5280
	s_waitcnt vmcnt(10)
	ds_write_b32 v78, v205 offset:5544
	s_waitcnt vmcnt(9)
	ds_write_b32 v78, v206 offset:5808
	s_waitcnt vmcnt(8)
	ds_write_b32 v78, v207 offset:6072
	s_waitcnt vmcnt(7)
	ds_write_b32 v78, v208 offset:6336
	s_waitcnt vmcnt(6)
	ds_write_b32 v78, v209 offset:6600
	s_waitcnt vmcnt(5)
	ds_write_b32 v78, v210 offset:6864
	s_waitcnt vmcnt(4)
	ds_write_b32 v78, v211 offset:7128
	s_waitcnt vmcnt(3)
	ds_write_b32 v78, v212 offset:7392
	s_waitcnt vmcnt(2)
	ds_write_b32 v78, v213 offset:7656
	s_waitcnt vmcnt(1)
	ds_write_b32 v78, v214 offset:7920
	s_waitcnt vmcnt(0)
	ds_write_b32 v78, v215 offset:8184
	s_waitcnt lgkmcnt(0)
; __device__ __forceinline__ void phase0(const Args& a, LAS unsigned char* lds, int tid, int wave, int lane, int vcu, int G, int pmask) {
;     ...
; #pragma unroll
;                 for (int ks = 0; ks < 2; ++ks) {
;                     bf16x8 ah[2], al[2];
; #pragma unroll
;                     for (int nt = 0; nt < 2; ++nt) { float v[8]; unsigned hb[8], lb[8];
; #pragma unroll
;                         for (int j = 0; j < 8; ++j) { v[j] = scr[(32 * ks + 8 * g + j) * 33 + 16 * nt + i16]; hb[j] = f2bf(v[j]); lb[j] = f2bf(v[j] - __uint_as_float(hb[j] << 16)); }
;                         u32x4 wh, wl; wh.x = hb[0] | (hb[1] << 16); wh.y = hb[2] | (hb[3] << 16); wh.z = hb[4] | (hb[5] << 16); wh.w = hb[6] | (hb[7] << 16);
;                         wl.x = lb[0] | (lb[1] << 16); wl.y = lb[2] | (lb[3] << 16); wl.z = lb[4] | (lb[5] << 16); wl.w = lb[6] | (lb[7] << 16);
;                         ah[nt] = __builtin_bit_cast(bf16x8, wh); al[nt] = __builtin_bit_cast(bf16x8, wl); }
; #pragma unroll
;                     for (int bt = 0; bt < 9; ++bt) {
;                         const int b = 16 * bt + i16; const int k = k0 + 32 * ks + 8 * g;
;                         f32x4 c0 = {0.f, 0.f, 0.f, 0.f}, c1 = c0;
;                         if (b < 129) { const float* cr = b == 0 ? cp + k : cs + (size_t)(b - 1) * DM + k; c0 = *(const f32x4*)cr; c1 = *(const f32x4*)(cr + 4); }
;                         unsigned hb[8], lb[8];
; #pragma unroll
;                         for (int j = 0; j < 8; ++j) { const float c = j < 4 ? c0[j & 3] : c1[j & 3]; const float sv = c * __builtin_amdgcn_rcpf(1.f + __expf(-c)); hb[j] = f2bf(sv); lb[j] = f2bf(sv - __uint_as_float(hb[j] << 16)); }
;                         u32x4 wh, wl; wh.x = hb[0] | (hb[1] << 16); wh.y = hb[2] | (hb[3] << 16); wh.z = hb[4] | (hb[5] << 16); wh.w = hb[6] | (hb[7] << 16);
;                         wl.x = lb[0] | (lb[1] << 16); wl.y = lb[2] | (lb[3] << 16); wl.z = lb[4] | (lb[5] << 16); wl.w = lb[6] | (lb[7] << 16);
;                         const bf16x8 bh = __builtin_bit_cast(bf16x8, wh), bl = __builtin_bit_cast(bf16x8, wl);
; #pragma unroll
;                         for (int nt = 0; nt < 2; ++nt) { acc[nt][bt] = mfma16(ah[nt], bh, acc[nt][bt]); acc[nt][bt] = mfma16(ah[nt], bl, acc[nt][bt]); acc[nt][bt] = mfma16(al[nt], bh, acc[nt][bt]); }
	s_load_dwordx16 s[60:75], s[0:1], 0x0
	v_and_b32_e32 v74, 15, v166
	v_lshrrev_b32_e32 v75, 4, v166
	v_and_b32_e32 v76, 31, v166
	v_lshlrev_b32_e32 v76, 2, v76
	v_sub_u32_e32 v76, v116, v76
	v_mul_u32_u24_e32 v77, 0x840, v75
	v_lshl_add_u32 v77, v74, 2, v77
	v_add_u32_e32 v76, v76, v77
	ds_read_b32 v180, v76
	ds_read_b32 v181, v76 offset:132
	ds_read_b32 v182, v76 offset:264
	ds_read_b32 v183, v76 offset:396
	ds_read_b32 v184, v76 offset:528
	ds_read_b32 v185, v76 offset:660
	ds_read_b32 v186, v76 offset:792
	ds_read_b32 v187, v76 offset:924
	ds_read_b32 v188, v76 offset:1056
	ds_read_b32 v189, v76 offset:1188
	ds_read_b32 v190, v76 offset:1320
	ds_read_b32 v191, v76 offset:1452
	ds_read_b32 v192, v76 offset:1584
	ds_read_b32 v193, v76 offset:1716
	ds_read_b32 v194, v76 offset:1848
	ds_read_b32 v195, v76 offset:1980
	ds_read_b32 v196, v76 offset:64
	ds_read_b32 v197, v76 offset:196
	ds_read_b32 v198, v76 offset:328
	ds_read_b32 v199, v76 offset:460
	ds_read_b32 v200, v76 offset:592
	ds_read_b32 v201, v76 offset:724
	ds_read_b32 v202, v76 offset:856
	ds_read_b32 v203, v76 offset:988
	ds_read_b32 v204, v76 offset:1120
	ds_read_b32 v205, v76 offset:1252
	ds_read_b32 v206, v76 offset:1384
	ds_read_b32 v207, v76 offset:1516
	ds_read_b32 v208, v76 offset:1648
	ds_read_b32 v209, v76 offset:1780
	ds_read_b32 v210, v76 offset:1912
	ds_read_b32 v211, v76 offset:2044
	v_lshl_add_u32 v78, v75, 4, s56
	v_lshlrev_b32_e32 v78, 2, v78
	v_mov_b32_e32 v79, 0
	v_add_u32_e32 v80, -1, v74
	v_ashrrev_i32_e32 v81, 31, v80
	v_lshlrev_b64 v[80:81], 12, v[80:81]
	v_lshl_add_u64 v[80:81], v[80:81], 0, v[78:79]
	v_lshl_add_u64 v[82:83], s[8:9], 0, v[80:81]
	v_lshl_add_u64 v[88:89], s[8:9], 0, v[78:79]
	s_mov_b64 s[88:89], 0x10000
	s_mov_b64 s[90:91], 0x7f000
	v_lshl_add_u64 v[88:89], v[88:89], 0, s[90:91]
	s_waitcnt lgkmcnt(0)
	v_lshl_add_u64 v[84:85], s[74:75], 0, v[78:79]
	v_cmp_eq_u32_e32 vcc, 0, v74
	s_nop 1
	v_cndmask_b32_e32 v86, v82, v84, vcc
	v_cndmask_b32_e32 v87, v83, v85, vcc
	global_load_dwordx4 v[146:149], v[86:87], off
	global_load_dwordx4 v[150:153], v[86:87], off offset:16
	global_load_dwordx4 v[154:157], v[86:87], off offset:32
	global_load_dwordx4 v[158:161], v[86:87], off offset:48
	v_lshl_add_u64 v[82:83], v[82:83], 0, s[88:89]
	global_load_dwordx4 v[212:215], v[82:83], off
	global_load_dwordx4 v[216:219], v[82:83], off offset:16
	global_load_dwordx4 v[220:223], v[82:83], off offset:32
	global_load_dwordx4 v[224:227], v[82:83], off offset:48
	s_waitcnt vmcnt(4)
	v_mul_f32_e32 v92, 0xbfb8aa3b, v146
	v_mul_f32_e32 v93, 0xbfb8aa3b, v147
	v_mul_f32_e32 v94, 0xbfb8aa3b, v148
	v_mul_f32_e32 v95, 0xbfb8aa3b, v149
	v_mul_f32_e32 v96, 0xbfb8aa3b, v150
	v_mul_f32_e32 v97, 0xbfb8aa3b, v151
	v_mul_f32_e32 v98, 0xbfb8aa3b, v152
	v_mul_f32_e32 v99, 0xbfb8aa3b, v153
	v_mul_f32_e32 v100, 0xbfb8aa3b, v154
	v_mul_f32_e32 v101, 0xbfb8aa3b, v155
	v_mul_f32_e32 v102, 0xbfb8aa3b, v156
	v_mul_f32_e32 v103, 0xbfb8aa3b, v157
	v_mul_f32_e32 v104, 0xbfb8aa3b, v158
	v_mul_f32_e32 v105, 0xbfb8aa3b, v159
	v_mul_f32_e32 v106, 0xbfb8aa3b, v160
	v_mul_f32_e32 v107, 0xbfb8aa3b, v161
	v_exp_f32_e32 v92, v92
	v_exp_f32_e32 v93, v93
	v_exp_f32_e32 v94, v94
	v_exp_f32_e32 v95, v95
	v_exp_f32_e32 v96, v96
	v_exp_f32_e32 v97, v97
	v_exp_f32_e32 v98, v98
	v_exp_f32_e32 v99, v99
	v_exp_f32_e32 v100, v100
	v_exp_f32_e32 v101, v101
	v_exp_f32_e32 v102, v102
	v_exp_f32_e32 v103, v103
	v_exp_f32_e32 v104, v104
	v_exp_f32_e32 v105, v105
	v_exp_f32_e32 v106, v106
	v_exp_f32_e32 v107, v107
	v_add_f32_e32 v92, 1.0, v92
	v_add_f32_e32 v93, 1.0, v93
	v_add_f32_e32 v94, 1.0, v94
	v_add_f32_e32 v95, 1.0, v95
	v_add_f32_e32 v96, 1.0, v96
	v_add_f32_e32 v97, 1.0, v97
	v_add_f32_e32 v98, 1.0, v98
	v_add_f32_e32 v99, 1.0, v99
	v_add_f32_e32 v100, 1.0, v100
	v_add_f32_e32 v101, 1.0, v101
	v_add_f32_e32 v102, 1.0, v102
	v_add_f32_e32 v103, 1.0, v103
	v_add_f32_e32 v104, 1.0, v104
	v_add_f32_e32 v105, 1.0, v105
	v_add_f32_e32 v106, 1.0, v106
	v_add_f32_e32 v107, 1.0, v107
	v_rcp_f32_e32 v92, v92
	v_rcp_f32_e32 v93, v93
	v_rcp_f32_e32 v94, v94
	v_rcp_f32_e32 v95, v95
	v_rcp_f32_e32 v96, v96
	v_rcp_f32_e32 v97, v97
	v_rcp_f32_e32 v98, v98
	v_rcp_f32_e32 v99, v99
	v_rcp_f32_e32 v100, v100
	v_rcp_f32_e32 v101, v101
	v_rcp_f32_e32 v102, v102
	v_rcp_f32_e32 v103, v103
	v_rcp_f32_e32 v104, v104
	v_rcp_f32_e32 v105, v105
	v_rcp_f32_e32 v106, v106
	v_rcp_f32_e32 v107, v107
	v_mul_f32_e32 v92, v146, v92
	v_mul_f32_e32 v93, v147, v93
	v_mul_f32_e32 v94, v148, v94
	v_mul_f32_e32 v95, v149, v95
	v_mul_f32_e32 v96, v150, v96
	v_mul_f32_e32 v97, v151, v97
	v_mul_f32_e32 v98, v152, v98
	v_mul_f32_e32 v99, v153, v99
	v_mul_f32_e32 v100, v154, v100
	v_mul_f32_e32 v101, v155, v101
	v_mul_f32_e32 v102, v156, v102
	v_mul_f32_e32 v103, v157, v103
	v_mul_f32_e32 v104, v158, v104
	v_mul_f32_e32 v105, v159, v105
	v_mul_f32_e32 v106, v160, v106
	v_mul_f32_e32 v107, v161, v107
	s_nop 1
	v_mfma_f32_16x16x4_f32 v[6:9], v180, v92, v[6:9]
	v_mfma_f32_16x16x4_f32 v[2:5], v196, v92, v[2:5]
	v_mfma_f32_16x16x4_f32 v[6:9], v181, v93, v[6:9]
	v_mfma_f32_16x16x4_f32 v[2:5], v197, v93, v[2:5]
	v_mfma_f32_16x16x4_f32 v[6:9], v182, v94, v[6:9]
	v_mfma_f32_16x16x4_f32 v[2:5], v198, v94, v[2:5]
	v_mfma_f32_16x16x4_f32 v[6:9], v183, v95, v[6:9]
	v_mfma_f32_16x16x4_f32 v[2:5], v199, v95, v[2:5]
	v_mfma_f32_16x16x4_f32 v[6:9], v184, v96, v[6:9]
	v_mfma_f32_16x16x4_f32 v[2:5], v200, v96, v[2:5]
	v_mfma_f32_16x16x4_f32 v[6:9], v185, v97, v[6:9]
	v_mfma_f32_16x16x4_f32 v[2:5], v201, v97, v[2:5]
	v_mfma_f32_16x16x4_f32 v[6:9], v186, v98, v[6:9]
	v_mfma_f32_16x16x4_f32 v[2:5], v202, v98, v[2:5]
	v_mfma_f32_16x16x4_f32 v[6:9], v187, v99, v[6:9]
	v_mfma_f32_16x16x4_f32 v[2:5], v203, v99, v[2:5]
	v_mfma_f32_16x16x4_f32 v[6:9], v188, v100, v[6:9]
	v_mfma_f32_16x16x4_f32 v[2:5], v204, v100, v[2:5]
	v_mfma_f32_16x16x4_f32 v[6:9], v189, v101, v[6:9]
	v_mfma_f32_16x16x4_f32 v[2:5], v205, v101, v[2:5]
	v_mfma_f32_16x16x4_f32 v[6:9], v190, v102, v[6:9]
	v_mfma_f32_16x16x4_f32 v[2:5], v206, v102, v[2:5]
	v_mfma_f32_16x16x4_f32 v[6:9], v191, v103, v[6:9]
	v_mfma_f32_16x16x4_f32 v[2:5], v207, v103, v[2:5]
	v_mfma_f32_16x16x4_f32 v[6:9], v192, v104, v[6:9]
	v_mfma_f32_16x16x4_f32 v[2:5], v208, v104, v[2:5]
	v_mfma_f32_16x16x4_f32 v[6:9], v193, v105, v[6:9]
	v_mfma_f32_16x16x4_f32 v[2:5], v209, v105, v[2:5]
	v_mfma_f32_16x16x4_f32 v[6:9], v194, v106, v[6:9]
	v_mfma_f32_16x16x4_f32 v[2:5], v210, v106, v[2:5]
	v_mfma_f32_16x16x4_f32 v[6:9], v195, v107, v[6:9]
	v_mfma_f32_16x16x4_f32 v[2:5], v211, v107, v[2:5]
	v_lshl_add_u64 v[82:83], v[82:83], 0, s[88:89]
	global_load_dwordx4 v[146:149], v[82:83], off
	global_load_dwordx4 v[150:153], v[82:83], off offset:16
	global_load_dwordx4 v[154:157], v[82:83], off offset:32
	global_load_dwordx4 v[158:161], v[82:83], off offset:48
	s_waitcnt vmcnt(4)
; __device__ __forceinline__ unsigned f2bf(float f) { unsigned u = __builtin_bit_cast(unsigned, f); return (u + 0x7fffu + ((u >> 16) & 1u)) >> 16; }
; __device__ __forceinline__ f32x4 mfma16(bf16x8 a, bf16x8 b, f32x4 c) { return __builtin_amdgcn_mfma_f32_16x16x32_bf16(a, b, c, 0, 0, 0); }
; __device__ __forceinline__ void phase0(const Args& a, LAS unsigned char* lds, int tid, int wave, int lane, int vcu, int G, int pmask) {
;     ...
;                     for (int bt = 0; bt < 9; ++bt) {
;                         const int b = 16 * bt + i16; const int k = k0 + 32 * ks + 8 * g;
;                         f32x4 c0 = {0.f, 0.f, 0.f, 0.f}, c1 = c0;
;                         if (b < 129) { const float* cr = b == 0 ? cp + k : cs + (size_t)(b - 1) * DM + k; c0 = *(const f32x4*)cr; c1 = *(const f32x4*)(cr + 4); }
;                         unsigned hb[8], lb[8];
; #pragma unroll
;                         for (int j = 0; j < 8; ++j) { const float c = j < 4 ? c0[j & 3] : c1[j & 3]; const float sv = c * __builtin_amdgcn_rcpf(1.f + __expf(-c)); hb[j] = f2bf(sv); lb[j] = f2bf(sv - __uint_as_float(hb[j] << 16)); }
;                         u32x4 wh, wl; wh.x = hb[0] | (hb[1] << 16); wh.y = hb[2] | (hb[3] << 16); wh.z = hb[4] | (hb[5] << 16); wh.w = hb[6] | (hb[7] << 16);
;                         wl.x = lb[0] | (lb[1] << 16); wl.y = lb[2] | (lb[3] << 16); wl.z = lb[4] | (lb[5] << 16); wl.w = lb[6] | (lb[7] << 16);
;                         const bf16x8 bh = __builtin_bit_cast(bf16x8, wh), bl = __builtin_bit_cast(bf16x8, wl);
; #pragma unroll
;                         for (int nt = 0; nt < 2; ++nt) { acc[nt][bt] = mfma16(ah[nt], bh, acc[nt][bt]); acc[nt][bt] = mfma16(ah[nt], bl, acc[nt][bt]); acc[nt][bt] = mfma16(al[nt], bh, acc[nt][bt]); }
	v_mul_f32_e32 v92, 0xbfb8aa3b, v212
	v_mul_f32_e32 v93, 0xbfb8aa3b, v213
	v_mul_f32_e32 v94, 0xbfb8aa3b, v214
	v_mul_f32_e32 v95, 0xbfb8aa3b, v215
	v_mul_f32_e32 v96, 0xbfb8aa3b, v216
	v_mul_f32_e32 v97, 0xbfb8aa3b, v217
	v_mul_f32_e32 v98, 0xbfb8aa3b, v218
	v_mul_f32_e32 v99, 0xbfb8aa3b, v219
	v_mul_f32_e32 v100, 0xbfb8aa3b, v220
	v_mul_f32_e32 v101, 0xbfb8aa3b, v221
	v_mul_f32_e32 v102, 0xbfb8aa3b, v222
	v_mul_f32_e32 v103, 0xbfb8aa3b, v223
	v_mul_f32_e32 v104, 0xbfb8aa3b, v224
	v_mul_f32_e32 v105, 0xbfb8aa3b, v225
	v_mul_f32_e32 v106, 0xbfb8aa3b, v226
	v_mul_f32_e32 v107, 0xbfb8aa3b, v227
	v_exp_f32_e32 v92, v92
	v_exp_f32_e32 v93, v93
	v_exp_f32_e32 v94, v94
	v_exp_f32_e32 v95, v95
	v_exp_f32_e32 v96, v96
	v_exp_f32_e32 v97, v97
	v_exp_f32_e32 v98, v98
	v_exp_f32_e32 v99, v99
	v_exp_f32_e32 v100, v100
	v_exp_f32_e32 v101, v101
	v_exp_f32_e32 v102, v102
	v_exp_f32_e32 v103, v103
	v_exp_f32_e32 v104, v104
	v_exp_f32_e32 v105, v105
	v_exp_f32_e32 v106, v106
	v_exp_f32_e32 v107, v107
	v_add_f32_e32 v92, 1.0, v92
	v_add_f32_e32 v93, 1.0, v93
	v_add_f32_e32 v94, 1.0, v94
	v_add_f32_e32 v95, 1.0, v95
	v_add_f32_e32 v96, 1.0, v96
	v_add_f32_e32 v97, 1.0, v97
	v_add_f32_e32 v98, 1.0, v98
	v_add_f32_e32 v99, 1.0, v99
	v_add_f32_e32 v100, 1.0, v100
	v_add_f32_e32 v101, 1.0, v101
	v_add_f32_e32 v102, 1.0, v102
	v_add_f32_e32 v103, 1.0, v103
	v_add_f32_e32 v104, 1.0, v104
	v_add_f32_e32 v105, 1.0, v105
	v_add_f32_e32 v106, 1.0, v106
	v_add_f32_e32 v107, 1.0, v107
	v_rcp_f32_e32 v92, v92
	v_rcp_f32_e32 v93, v93
	v_rcp_f32_e32 v94, v94
	v_rcp_f32_e32 v95, v95
	v_rcp_f32_e32 v96, v96
	v_rcp_f32_e32 v97, v97
	v_rcp_f32_e32 v98, v98
	v_rcp_f32_e32 v99, v99
	v_rcp_f32_e32 v100, v100
	v_rcp_f32_e32 v101, v101
	v_rcp_f32_e32 v102, v102
	v_rcp_f32_e32 v103, v103
	v_rcp_f32_e32 v104, v104
	v_rcp_f32_e32 v105, v105
	v_rcp_f32_e32 v106, v106
	v_rcp_f32_e32 v107, v107
	v_mul_f32_e32 v92, v212, v92
	v_mul_f32_e32 v93, v213, v93
	v_mul_f32_e32 v94, v214, v94
	v_mul_f32_e32 v95, v215, v95
	v_mul_f32_e32 v96, v216, v96
	v_mul_f32_e32 v97, v217, v97
	v_mul_f32_e32 v98, v218, v98
	v_mul_f32_e32 v99, v219, v99
	v_mul_f32_e32 v100, v220, v100
	v_mul_f32_e32 v101, v221, v101
	v_mul_f32_e32 v102, v222, v102
	v_mul_f32_e32 v103, v223, v103
	v_mul_f32_e32 v104, v224, v104
	v_mul_f32_e32 v105, v225, v105
	v_mul_f32_e32 v106, v226, v106
	v_mul_f32_e32 v107, v227, v107
	s_nop 1
	v_mfma_f32_16x16x4_f32 v[50:53], v180, v92, v[50:53]
	v_mfma_f32_16x16x4_f32 v[54:57], v196, v92, v[54:57]
	v_mfma_f32_16x16x4_f32 v[50:53], v181, v93, v[50:53]
	v_mfma_f32_16x16x4_f32 v[54:57], v197, v93, v[54:57]
	v_mfma_f32_16x16x4_f32 v[50:53], v182, v94, v[50:53]
	v_mfma_f32_16x16x4_f32 v[54:57], v198, v94, v[54:57]
	v_mfma_f32_16x16x4_f32 v[50:53], v183, v95, v[50:53]
	v_mfma_f32_16x16x4_f32 v[54:57], v199, v95, v[54:57]
	v_mfma_f32_16x16x4_f32 v[50:53], v184, v96, v[50:53]
	v_mfma_f32_16x16x4_f32 v[54:57], v200, v96, v[54:57]
	v_mfma_f32_16x16x4_f32 v[50:53], v185, v97, v[50:53]
	v_mfma_f32_16x16x4_f32 v[54:57], v201, v97, v[54:57]
	v_mfma_f32_16x16x4_f32 v[50:53], v186, v98, v[50:53]
	v_mfma_f32_16x16x4_f32 v[54:57], v202, v98, v[54:57]
	v_mfma_f32_16x16x4_f32 v[50:53], v187, v99, v[50:53]
	v_mfma_f32_16x16x4_f32 v[54:57], v203, v99, v[54:57]
	v_mfma_f32_16x16x4_f32 v[50:53], v188, v100, v[50:53]
	v_mfma_f32_16x16x4_f32 v[54:57], v204, v100, v[54:57]
	v_mfma_f32_16x16x4_f32 v[50:53], v189, v101, v[50:53]
	v_mfma_f32_16x16x4_f32 v[54:57], v205, v101, v[54:57]
	v_mfma_f32_16x16x4_f32 v[50:53], v190, v102, v[50:53]
	v_mfma_f32_16x16x4_f32 v[54:57], v206, v102, v[54:57]
	v_mfma_f32_16x16x4_f32 v[50:53], v191, v103, v[50:53]
	v_mfma_f32_16x16x4_f32 v[54:57], v207, v103, v[54:57]
	v_mfma_f32_16x16x4_f32 v[50:53], v192, v104, v[50:53]
	v_mfma_f32_16x16x4_f32 v[54:57], v208, v104, v[54:57]
	v_mfma_f32_16x16x4_f32 v[50:53], v193, v105, v[50:53]
	v_mfma_f32_16x16x4_f32 v[54:57], v209, v105, v[54:57]
	v_mfma_f32_16x16x4_f32 v[50:53], v194, v106, v[50:53]
	v_mfma_f32_16x16x4_f32 v[54:57], v210, v106, v[54:57]
	v_mfma_f32_16x16x4_f32 v[50:53], v195, v107, v[50:53]
	v_mfma_f32_16x16x4_f32 v[54:57], v211, v107, v[54:57]
	v_lshl_add_u64 v[82:83], v[82:83], 0, s[88:89]
	global_load_dwordx4 v[212:215], v[82:83], off
	global_load_dwordx4 v[216:219], v[82:83], off offset:16
	global_load_dwordx4 v[220:223], v[82:83], off offset:32
	global_load_dwordx4 v[224:227], v[82:83], off offset:48
	s_waitcnt vmcnt(4)
; __device__ __forceinline__ unsigned f2bf(float f) { unsigned u = __builtin_bit_cast(unsigned, f); return (u + 0x7fffu + ((u >> 16) & 1u)) >> 16; }
; __device__ __forceinline__ f32x4 mfma16(bf16x8 a, bf16x8 b, f32x4 c) { return __builtin_amdgcn_mfma_f32_16x16x32_bf16(a, b, c, 0, 0, 0); }
; __device__ __forceinline__ void phase0(const Args& a, LAS unsigned char* lds, int tid, int wave, int lane, int vcu, int G, int pmask) {
;     ...
;                     for (int bt = 0; bt < 9; ++bt) {
;                         const int b = 16 * bt + i16; const int k = k0 + 32 * ks + 8 * g;
;                         f32x4 c0 = {0.f, 0.f, 0.f, 0.f}, c1 = c0;
;                         if (b < 129) { const float* cr = b == 0 ? cp + k : cs + (size_t)(b - 1) * DM + k; c0 = *(const f32x4*)cr; c1 = *(const f32x4*)(cr + 4); }
;                         unsigned hb[8], lb[8];
; #pragma unroll
;                         for (int j = 0; j < 8; ++j) { const float c = j < 4 ? c0[j & 3] : c1[j & 3]; const float sv = c * __builtin_amdgcn_rcpf(1.f + __expf(-c)); hb[j] = f2bf(sv); lb[j] = f2bf(sv - __uint_as_float(hb[j] << 16)); }
;                         u32x4 wh, wl; wh.x = hb[0] | (hb[1] << 16); wh.y = hb[2] | (hb[3] << 16); wh.z = hb[4] | (hb[5] << 16); wh.w = hb[6] | (hb[7] << 16);
;                         wl.x = lb[0] | (lb[1] << 16); wl.y = lb[2] | (lb[3] << 16); wl.z = lb[4] | (lb[5] << 16); wl.w = lb[6] | (lb[7] << 16);
;                         const bf16x8 bh = __builtin_bit_cast(bf16x8, wh), bl = __builtin_bit_cast(bf16x8, wl);
; #pragma unroll
;                         for (int nt = 0; nt < 2; ++nt) { acc[nt][bt] = mfma16(ah[nt], bh, acc[nt][bt]); acc[nt][bt] = mfma16(ah[nt], bl, acc[nt][bt]); acc[nt][bt] = mfma16(al[nt], bh, acc[nt][bt]); }
	v_mul_f32_e32 v92, 0xbfb8aa3b, v146
	v_mul_f32_e32 v93, 0xbfb8aa3b, v147
	v_mul_f32_e32 v94, 0xbfb8aa3b, v148
	v_mul_f32_e32 v95, 0xbfb8aa3b, v149
	v_mul_f32_e32 v96, 0xbfb8aa3b, v150
	v_mul_f32_e32 v97, 0xbfb8aa3b, v151
	v_mul_f32_e32 v98, 0xbfb8aa3b, v152
	v_mul_f32_e32 v99, 0xbfb8aa3b, v153
	v_mul_f32_e32 v100, 0xbfb8aa3b, v154
	v_mul_f32_e32 v101, 0xbfb8aa3b, v155
	v_mul_f32_e32 v102, 0xbfb8aa3b, v156
	v_mul_f32_e32 v103, 0xbfb8aa3b, v157
	v_mul_f32_e32 v104, 0xbfb8aa3b, v158
	v_mul_f32_e32 v105, 0xbfb8aa3b, v159
	v_mul_f32_e32 v106, 0xbfb8aa3b, v160
	v_mul_f32_e32 v107, 0xbfb8aa3b, v161
	v_exp_f32_e32 v92, v92
	v_exp_f32_e32 v93, v93
	v_exp_f32_e32 v94, v94
	v_exp_f32_e32 v95, v95
	v_exp_f32_e32 v96, v96
	v_exp_f32_e32 v97, v97
	v_exp_f32_e32 v98, v98
	v_exp_f32_e32 v99, v99
	v_exp_f32_e32 v100, v100
	v_exp_f32_e32 v101, v101
	v_exp_f32_e32 v102, v102
	v_exp_f32_e32 v103, v103
	v_exp_f32_e32 v104, v104
	v_exp_f32_e32 v105, v105
	v_exp_f32_e32 v106, v106
	v_exp_f32_e32 v107, v107
	v_add_f32_e32 v92, 1.0, v92
	v_add_f32_e32 v93, 1.0, v93
	v_add_f32_e32 v94, 1.0, v94
	v_add_f32_e32 v95, 1.0, v95
	v_add_f32_e32 v96, 1.0, v96
	v_add_f32_e32 v97, 1.0, v97
	v_add_f32_e32 v98, 1.0, v98
	v_add_f32_e32 v99, 1.0, v99
	v_add_f32_e32 v100, 1.0, v100
	v_add_f32_e32 v101, 1.0, v101
	v_add_f32_e32 v102, 1.0, v102
	v_add_f32_e32 v103, 1.0, v103
	v_add_f32_e32 v104, 1.0, v104
	v_add_f32_e32 v105, 1.0, v105
	v_add_f32_e32 v106, 1.0, v106
	v_add_f32_e32 v107, 1.0, v107
	v_rcp_f32_e32 v92, v92
	v_rcp_f32_e32 v93, v93
	v_rcp_f32_e32 v94, v94
	v_rcp_f32_e32 v95, v95
	v_rcp_f32_e32 v96, v96
	v_rcp_f32_e32 v97, v97
	v_rcp_f32_e32 v98, v98
	v_rcp_f32_e32 v99, v99
	v_rcp_f32_e32 v100, v100
	v_rcp_f32_e32 v101, v101
	v_rcp_f32_e32 v102, v102
	v_rcp_f32_e32 v103, v103
	v_rcp_f32_e32 v104, v104
	v_rcp_f32_e32 v105, v105
	v_rcp_f32_e32 v106, v106
	v_rcp_f32_e32 v107, v107
	v_mul_f32_e32 v92, v146, v92
	v_mul_f32_e32 v93, v147, v93
	v_mul_f32_e32 v94, v148, v94
	v_mul_f32_e32 v95, v149, v95
	v_mul_f32_e32 v96, v150, v96
	v_mul_f32_e32 v97, v151, v97
	v_mul_f32_e32 v98, v152, v98
	v_mul_f32_e32 v99, v153, v99
	v_mul_f32_e32 v100, v154, v100
	v_mul_f32_e32 v101, v155, v101
	v_mul_f32_e32 v102, v156, v102
	v_mul_f32_e32 v103, v157, v103
	v_mul_f32_e32 v104, v158, v104
	v_mul_f32_e32 v105, v159, v105
	v_mul_f32_e32 v106, v160, v106
	v_mul_f32_e32 v107, v161, v107
	s_nop 1
	v_mfma_f32_16x16x4_f32 v[66:69], v180, v92, v[66:69]
	v_mfma_f32_16x16x4_f32 v[70:73], v196, v92, v[70:73]
	v_mfma_f32_16x16x4_f32 v[66:69], v181, v93, v[66:69]
	v_mfma_f32_16x16x4_f32 v[70:73], v197, v93, v[70:73]
	v_mfma_f32_16x16x4_f32 v[66:69], v182, v94, v[66:69]
	v_mfma_f32_16x16x4_f32 v[70:73], v198, v94, v[70:73]
	v_mfma_f32_16x16x4_f32 v[66:69], v183, v95, v[66:69]
	v_mfma_f32_16x16x4_f32 v[70:73], v199, v95, v[70:73]
	v_mfma_f32_16x16x4_f32 v[66:69], v184, v96, v[66:69]
	v_mfma_f32_16x16x4_f32 v[70:73], v200, v96, v[70:73]
	v_mfma_f32_16x16x4_f32 v[66:69], v185, v97, v[66:69]
	v_mfma_f32_16x16x4_f32 v[70:73], v201, v97, v[70:73]
	v_mfma_f32_16x16x4_f32 v[66:69], v186, v98, v[66:69]
	v_mfma_f32_16x16x4_f32 v[70:73], v202, v98, v[70:73]
	v_mfma_f32_16x16x4_f32 v[66:69], v187, v99, v[66:69]
	v_mfma_f32_16x16x4_f32 v[70:73], v203, v99, v[70:73]
	v_mfma_f32_16x16x4_f32 v[66:69], v188, v100, v[66:69]
	v_mfma_f32_16x16x4_f32 v[70:73], v204, v100, v[70:73]
	v_mfma_f32_16x16x4_f32 v[66:69], v189, v101, v[66:69]
	v_mfma_f32_16x16x4_f32 v[70:73], v205, v101, v[70:73]
	v_mfma_f32_16x16x4_f32 v[66:69], v190, v102, v[66:69]
	v_mfma_f32_16x16x4_f32 v[70:73], v206, v102, v[70:73]
	v_mfma_f32_16x16x4_f32 v[66:69], v191, v103, v[66:69]
	v_mfma_f32_16x16x4_f32 v[70:73], v207, v103, v[70:73]
	v_mfma_f32_16x16x4_f32 v[66:69], v192, v104, v[66:69]
	v_mfma_f32_16x16x4_f32 v[70:73], v208, v104, v[70:73]
	v_mfma_f32_16x16x4_f32 v[66:69], v193, v105, v[66:69]
	v_mfma_f32_16x16x4_f32 v[70:73], v209, v105, v[70:73]
	v_mfma_f32_16x16x4_f32 v[66:69], v194, v106, v[66:69]
	v_mfma_f32_16x16x4_f32 v[70:73], v210, v106, v[70:73]
	v_mfma_f32_16x16x4_f32 v[66:69], v195, v107, v[66:69]
	v_mfma_f32_16x16x4_f32 v[70:73], v211, v107, v[70:73]
	v_lshl_add_u64 v[82:83], v[82:83], 0, s[88:89]
	global_load_dwordx4 v[146:149], v[82:83], off
	global_load_dwordx4 v[150:153], v[82:83], off offset:16
	global_load_dwordx4 v[154:157], v[82:83], off offset:32
	global_load_dwordx4 v[158:161], v[82:83], off offset:48
	s_waitcnt vmcnt(4)
; __device__ __forceinline__ unsigned f2bf(float f) { unsigned u = __builtin_bit_cast(unsigned, f); return (u + 0x7fffu + ((u >> 16) & 1u)) >> 16; }
; __device__ __forceinline__ f32x4 mfma16(bf16x8 a, bf16x8 b, f32x4 c) { return __builtin_amdgcn_mfma_f32_16x16x32_bf16(a, b, c, 0, 0, 0); }
; __device__ __forceinline__ void phase0(const Args& a, LAS unsigned char* lds, int tid, int wave, int lane, int vcu, int G, int pmask) {
;     ...
;                     for (int bt = 0; bt < 9; ++bt) {
;                         const int b = 16 * bt + i16; const int k = k0 + 32 * ks + 8 * g;
;                         f32x4 c0 = {0.f, 0.f, 0.f, 0.f}, c1 = c0;
;                         if (b < 129) { const float* cr = b == 0 ? cp + k : cs + (size_t)(b - 1) * DM + k; c0 = *(const f32x4*)cr; c1 = *(const f32x4*)(cr + 4); }
;                         unsigned hb[8], lb[8];
; #pragma unroll
;                         for (int j = 0; j < 8; ++j) { const float c = j < 4 ? c0[j & 3] : c1[j & 3]; const float sv = c * __builtin_amdgcn_rcpf(1.f + __expf(-c)); hb[j] = f2bf(sv); lb[j] = f2bf(sv - __uint_as_float(hb[j] << 16)); }
;                         u32x4 wh, wl; wh.x = hb[0] | (hb[1] << 16); wh.y = hb[2] | (hb[3] << 16); wh.z = hb[4] | (hb[5] << 16); wh.w = hb[6] | (hb[7] << 16);
;                         wl.x = lb[0] | (lb[1] << 16); wl.y = lb[2] | (lb[3] << 16); wl.z = lb[4] | (lb[5] << 16); wl.w = lb[6] | (lb[7] << 16);
;                         const bf16x8 bh = __builtin_bit_cast(bf16x8, wh), bl = __builtin_bit_cast(bf16x8, wl);
; #pragma unroll
;                         for (int nt = 0; nt < 2; ++nt) { acc[nt][bt] = mfma16(ah[nt], bh, acc[nt][bt]); acc[nt][bt] = mfma16(ah[nt], bl, acc[nt][bt]); acc[nt][bt] = mfma16(al[nt], bh, acc[nt][bt]); }
	v_mul_f32_e32 v92, 0xbfb8aa3b, v212
	v_mul_f32_e32 v93, 0xbfb8aa3b, v213
	v_mul_f32_e32 v94, 0xbfb8aa3b, v214
	v_mul_f32_e32 v95, 0xbfb8aa3b, v215
	v_mul_f32_e32 v96, 0xbfb8aa3b, v216
	v_mul_f32_e32 v97, 0xbfb8aa3b, v217
	v_mul_f32_e32 v98, 0xbfb8aa3b, v218
	v_mul_f32_e32 v99, 0xbfb8aa3b, v219
	v_mul_f32_e32 v100, 0xbfb8aa3b, v220
	v_mul_f32_e32 v101, 0xbfb8aa3b, v221
	v_mul_f32_e32 v102, 0xbfb8aa3b, v222
	v_mul_f32_e32 v103, 0xbfb8aa3b, v223
	v_mul_f32_e32 v104, 0xbfb8aa3b, v224
	v_mul_f32_e32 v105, 0xbfb8aa3b, v225
	v_mul_f32_e32 v106, 0xbfb8aa3b, v226
	v_mul_f32_e32 v107, 0xbfb8aa3b, v227
	v_exp_f32_e32 v92, v92
	v_exp_f32_e32 v93, v93
	v_exp_f32_e32 v94, v94
	v_exp_f32_e32 v95, v95
	v_exp_f32_e32 v96, v96
	v_exp_f32_e32 v97, v97
	v_exp_f32_e32 v98, v98
	v_exp_f32_e32 v99, v99
	v_exp_f32_e32 v100, v100
	v_exp_f32_e32 v101, v101
	v_exp_f32_e32 v102, v102
	v_exp_f32_e32 v103, v103
	v_exp_f32_e32 v104, v104
	v_exp_f32_e32 v105, v105
	v_exp_f32_e32 v106, v106
	v_exp_f32_e32 v107, v107
	v_add_f32_e32 v92, 1.0, v92
	v_add_f32_e32 v93, 1.0, v93
	v_add_f32_e32 v94, 1.0, v94
	v_add_f32_e32 v95, 1.0, v95
	v_add_f32_e32 v96, 1.0, v96
	v_add_f32_e32 v97, 1.0, v97
	v_add_f32_e32 v98, 1.0, v98
	v_add_f32_e32 v99, 1.0, v99
	v_add_f32_e32 v100, 1.0, v100
	v_add_f32_e32 v101, 1.0, v101
	v_add_f32_e32 v102, 1.0, v102
	v_add_f32_e32 v103, 1.0, v103
	v_add_f32_e32 v104, 1.0, v104
	v_add_f32_e32 v105, 1.0, v105
	v_add_f32_e32 v106, 1.0, v106
	v_add_f32_e32 v107, 1.0, v107
	v_rcp_f32_e32 v92, v92
	v_rcp_f32_e32 v93, v93
	v_rcp_f32_e32 v94, v94
	v_rcp_f32_e32 v95, v95
	v_rcp_f32_e32 v96, v96
	v_rcp_f32_e32 v97, v97
	v_rcp_f32_e32 v98, v98
	v_rcp_f32_e32 v99, v99
	v_rcp_f32_e32 v100, v100
	v_rcp_f32_e32 v101, v101
	v_rcp_f32_e32 v102, v102
	v_rcp_f32_e32 v103, v103
	v_rcp_f32_e32 v104, v104
	v_rcp_f32_e32 v105, v105
	v_rcp_f32_e32 v106, v106
	v_rcp_f32_e32 v107, v107
	v_mul_f32_e32 v92, v212, v92
	v_mul_f32_e32 v93, v213, v93
	v_mul_f32_e32 v94, v214, v94
	v_mul_f32_e32 v95, v215, v95
	v_mul_f32_e32 v96, v216, v96
	v_mul_f32_e32 v97, v217, v97
	v_mul_f32_e32 v98, v218, v98
	v_mul_f32_e32 v99, v219, v99
	v_mul_f32_e32 v100, v220, v100
	v_mul_f32_e32 v101, v221, v101
	v_mul_f32_e32 v102, v222, v102
	v_mul_f32_e32 v103, v223, v103
	v_mul_f32_e32 v104, v224, v104
	v_mul_f32_e32 v105, v225, v105
	v_mul_f32_e32 v106, v226, v106
	v_mul_f32_e32 v107, v227, v107
	s_nop 1
	v_mfma_f32_16x16x4_f32 v[42:45], v180, v92, v[42:45]
	v_mfma_f32_16x16x4_f32 v[34:37], v196, v92, v[34:37]
	v_mfma_f32_16x16x4_f32 v[42:45], v181, v93, v[42:45]
	v_mfma_f32_16x16x4_f32 v[34:37], v197, v93, v[34:37]
	v_mfma_f32_16x16x4_f32 v[42:45], v182, v94, v[42:45]
	v_mfma_f32_16x16x4_f32 v[34:37], v198, v94, v[34:37]
	v_mfma_f32_16x16x4_f32 v[42:45], v183, v95, v[42:45]
	v_mfma_f32_16x16x4_f32 v[34:37], v199, v95, v[34:37]
	v_mfma_f32_16x16x4_f32 v[42:45], v184, v96, v[42:45]
	v_mfma_f32_16x16x4_f32 v[34:37], v200, v96, v[34:37]
	v_mfma_f32_16x16x4_f32 v[42:45], v185, v97, v[42:45]
	v_mfma_f32_16x16x4_f32 v[34:37], v201, v97, v[34:37]
	v_mfma_f32_16x16x4_f32 v[42:45], v186, v98, v[42:45]
	v_mfma_f32_16x16x4_f32 v[34:37], v202, v98, v[34:37]
	v_mfma_f32_16x16x4_f32 v[42:45], v187, v99, v[42:45]
	v_mfma_f32_16x16x4_f32 v[34:37], v203, v99, v[34:37]
	v_mfma_f32_16x16x4_f32 v[42:45], v188, v100, v[42:45]
	v_mfma_f32_16x16x4_f32 v[34:37], v204, v100, v[34:37]
	v_mfma_f32_16x16x4_f32 v[42:45], v189, v101, v[42:45]
	v_mfma_f32_16x16x4_f32 v[34:37], v205, v101, v[34:37]
	v_mfma_f32_16x16x4_f32 v[42:45], v190, v102, v[42:45]
	v_mfma_f32_16x16x4_f32 v[34:37], v206, v102, v[34:37]
	v_mfma_f32_16x16x4_f32 v[42:45], v191, v103, v[42:45]
	v_mfma_f32_16x16x4_f32 v[34:37], v207, v103, v[34:37]
	v_mfma_f32_16x16x4_f32 v[42:45], v192, v104, v[42:45]
	v_mfma_f32_16x16x4_f32 v[34:37], v208, v104, v[34:37]
	v_mfma_f32_16x16x4_f32 v[42:45], v193, v105, v[42:45]
	v_mfma_f32_16x16x4_f32 v[34:37], v209, v105, v[34:37]
	v_mfma_f32_16x16x4_f32 v[42:45], v194, v106, v[42:45]
	v_mfma_f32_16x16x4_f32 v[34:37], v210, v106, v[34:37]
	v_mfma_f32_16x16x4_f32 v[42:45], v195, v107, v[42:45]
	v_mfma_f32_16x16x4_f32 v[34:37], v211, v107, v[34:37]
	v_lshl_add_u64 v[82:83], v[82:83], 0, s[88:89]
	global_load_dwordx4 v[212:215], v[82:83], off
	global_load_dwordx4 v[216:219], v[82:83], off offset:16
	global_load_dwordx4 v[220:223], v[82:83], off offset:32
	global_load_dwordx4 v[224:227], v[82:83], off offset:48
	s_waitcnt vmcnt(4)
; __device__ __forceinline__ unsigned f2bf(float f) { unsigned u = __builtin_bit_cast(unsigned, f); return (u + 0x7fffu + ((u >> 16) & 1u)) >> 16; }
; __device__ __forceinline__ f32x4 mfma16(bf16x8 a, bf16x8 b, f32x4 c) { return __builtin_amdgcn_mfma_f32_16x16x32_bf16(a, b, c, 0, 0, 0); }
; __device__ __forceinline__ void phase0(const Args& a, LAS unsigned char* lds, int tid, int wave, int lane, int vcu, int G, int pmask) {
;     ...
;                     for (int bt = 0; bt < 9; ++bt) {
;                         const int b = 16 * bt + i16; const int k = k0 + 32 * ks + 8 * g;
;                         f32x4 c0 = {0.f, 0.f, 0.f, 0.f}, c1 = c0;
;                         if (b < 129) { const float* cr = b == 0 ? cp + k : cs + (size_t)(b - 1) * DM + k; c0 = *(const f32x4*)cr; c1 = *(const f32x4*)(cr + 4); }
;                         unsigned hb[8], lb[8];
; #pragma unroll
;                         for (int j = 0; j < 8; ++j) { const float c = j < 4 ? c0[j & 3] : c1[j & 3]; const float sv = c * __builtin_amdgcn_rcpf(1.f + __expf(-c)); hb[j] = f2bf(sv); lb[j] = f2bf(sv - __uint_as_float(hb[j] << 16)); }
;                         u32x4 wh, wl; wh.x = hb[0] | (hb[1] << 16); wh.y = hb[2] | (hb[3] << 16); wh.z = hb[4] | (hb[5] << 16); wh.w = hb[6] | (hb[7] << 16);
;                         wl.x = lb[0] | (lb[1] << 16); wl.y = lb[2] | (lb[3] << 16); wl.z = lb[4] | (lb[5] << 16); wl.w = lb[6] | (lb[7] << 16);
;                         const bf16x8 bh = __builtin_bit_cast(bf16x8, wh), bl = __builtin_bit_cast(bf16x8, wl);
; #pragma unroll
;                         for (int nt = 0; nt < 2; ++nt) { acc[nt][bt] = mfma16(ah[nt], bh, acc[nt][bt]); acc[nt][bt] = mfma16(ah[nt], bl, acc[nt][bt]); acc[nt][bt] = mfma16(al[nt], bh, acc[nt][bt]); }
	v_mul_f32_e32 v92, 0xbfb8aa3b, v146
	v_mul_f32_e32 v93, 0xbfb8aa3b, v147
	v_mul_f32_e32 v94, 0xbfb8aa3b, v148
	v_mul_f32_e32 v95, 0xbfb8aa3b, v149
	v_mul_f32_e32 v96, 0xbfb8aa3b, v150
	v_mul_f32_e32 v97, 0xbfb8aa3b, v151
	v_mul_f32_e32 v98, 0xbfb8aa3b, v152
	v_mul_f32_e32 v99, 0xbfb8aa3b, v153
	v_mul_f32_e32 v100, 0xbfb8aa3b, v154
	v_mul_f32_e32 v101, 0xbfb8aa3b, v155
	v_mul_f32_e32 v102, 0xbfb8aa3b, v156
	v_mul_f32_e32 v103, 0xbfb8aa3b, v157
	v_mul_f32_e32 v104, 0xbfb8aa3b, v158
	v_mul_f32_e32 v105, 0xbfb8aa3b, v159
	v_mul_f32_e32 v106, 0xbfb8aa3b, v160
	v_mul_f32_e32 v107, 0xbfb8aa3b, v161
	v_exp_f32_e32 v92, v92
	v_exp_f32_e32 v93, v93
	v_exp_f32_e32 v94, v94
	v_exp_f32_e32 v95, v95
	v_exp_f32_e32 v96, v96
	v_exp_f32_e32 v97, v97
	v_exp_f32_e32 v98, v98
	v_exp_f32_e32 v99, v99
	v_exp_f32_e32 v100, v100
	v_exp_f32_e32 v101, v101
	v_exp_f32_e32 v102, v102
	v_exp_f32_e32 v103, v103
	v_exp_f32_e32 v104, v104
	v_exp_f32_e32 v105, v105
	v_exp_f32_e32 v106, v106
	v_exp_f32_e32 v107, v107
	v_add_f32_e32 v92, 1.0, v92
	v_add_f32_e32 v93, 1.0, v93
	v_add_f32_e32 v94, 1.0, v94
	v_add_f32_e32 v95, 1.0, v95
	v_add_f32_e32 v96, 1.0, v96
	v_add_f32_e32 v97, 1.0, v97
	v_add_f32_e32 v98, 1.0, v98
	v_add_f32_e32 v99, 1.0, v99
	v_add_f32_e32 v100, 1.0, v100
	v_add_f32_e32 v101, 1.0, v101
	v_add_f32_e32 v102, 1.0, v102
	v_add_f32_e32 v103, 1.0, v103
	v_add_f32_e32 v104, 1.0, v104
	v_add_f32_e32 v105, 1.0, v105
	v_add_f32_e32 v106, 1.0, v106
	v_add_f32_e32 v107, 1.0, v107
	v_rcp_f32_e32 v92, v92
	v_rcp_f32_e32 v93, v93
	v_rcp_f32_e32 v94, v94
	v_rcp_f32_e32 v95, v95
	v_rcp_f32_e32 v96, v96
	v_rcp_f32_e32 v97, v97
	v_rcp_f32_e32 v98, v98
	v_rcp_f32_e32 v99, v99
	v_rcp_f32_e32 v100, v100
	v_rcp_f32_e32 v101, v101
	v_rcp_f32_e32 v102, v102
	v_rcp_f32_e32 v103, v103
	v_rcp_f32_e32 v104, v104
	v_rcp_f32_e32 v105, v105
	v_rcp_f32_e32 v106, v106
	v_rcp_f32_e32 v107, v107
	v_mul_f32_e32 v92, v146, v92
	v_mul_f32_e32 v93, v147, v93
	v_mul_f32_e32 v94, v148, v94
	v_mul_f32_e32 v95, v149, v95
	v_mul_f32_e32 v96, v150, v96
	v_mul_f32_e32 v97, v151, v97
	v_mul_f32_e32 v98, v152, v98
	v_mul_f32_e32 v99, v153, v99
	v_mul_f32_e32 v100, v154, v100
	v_mul_f32_e32 v101, v155, v101
	v_mul_f32_e32 v102, v156, v102
	v_mul_f32_e32 v103, v157, v103
	v_mul_f32_e32 v104, v158, v104
	v_mul_f32_e32 v105, v159, v105
	v_mul_f32_e32 v106, v160, v106
	v_mul_f32_e32 v107, v161, v107
	s_nop 1
	v_mfma_f32_16x16x4_f32 v[30:33], v180, v92, v[30:33]
	v_mfma_f32_16x16x4_f32 v[18:21], v196, v92, v[18:21]
	v_mfma_f32_16x16x4_f32 v[30:33], v181, v93, v[30:33]
	v_mfma_f32_16x16x4_f32 v[18:21], v197, v93, v[18:21]
	v_mfma_f32_16x16x4_f32 v[30:33], v182, v94, v[30:33]
	v_mfma_f32_16x16x4_f32 v[18:21], v198, v94, v[18:21]
	v_mfma_f32_16x16x4_f32 v[30:33], v183, v95, v[30:33]
	v_mfma_f32_16x16x4_f32 v[18:21], v199, v95, v[18:21]
	v_mfma_f32_16x16x4_f32 v[30:33], v184, v96, v[30:33]
	v_mfma_f32_16x16x4_f32 v[18:21], v200, v96, v[18:21]
	v_mfma_f32_16x16x4_f32 v[30:33], v185, v97, v[30:33]
	v_mfma_f32_16x16x4_f32 v[18:21], v201, v97, v[18:21]
	v_mfma_f32_16x16x4_f32 v[30:33], v186, v98, v[30:33]
	v_mfma_f32_16x16x4_f32 v[18:21], v202, v98, v[18:21]
	v_mfma_f32_16x16x4_f32 v[30:33], v187, v99, v[30:33]
	v_mfma_f32_16x16x4_f32 v[18:21], v203, v99, v[18:21]
	v_mfma_f32_16x16x4_f32 v[30:33], v188, v100, v[30:33]
	v_mfma_f32_16x16x4_f32 v[18:21], v204, v100, v[18:21]
	v_mfma_f32_16x16x4_f32 v[30:33], v189, v101, v[30:33]
	v_mfma_f32_16x16x4_f32 v[18:21], v205, v101, v[18:21]
	v_mfma_f32_16x16x4_f32 v[30:33], v190, v102, v[30:33]
	v_mfma_f32_16x16x4_f32 v[18:21], v206, v102, v[18:21]
	v_mfma_f32_16x16x4_f32 v[30:33], v191, v103, v[30:33]
	v_mfma_f32_16x16x4_f32 v[18:21], v207, v103, v[18:21]
	v_mfma_f32_16x16x4_f32 v[30:33], v192, v104, v[30:33]
	v_mfma_f32_16x16x4_f32 v[18:21], v208, v104, v[18:21]
	v_mfma_f32_16x16x4_f32 v[30:33], v193, v105, v[30:33]
	v_mfma_f32_16x16x4_f32 v[18:21], v209, v105, v[18:21]
	v_mfma_f32_16x16x4_f32 v[30:33], v194, v106, v[30:33]
	v_mfma_f32_16x16x4_f32 v[18:21], v210, v106, v[18:21]
	v_mfma_f32_16x16x4_f32 v[30:33], v195, v107, v[30:33]
	v_mfma_f32_16x16x4_f32 v[18:21], v211, v107, v[18:21]
	v_lshl_add_u64 v[82:83], v[82:83], 0, s[88:89]
	global_load_dwordx4 v[146:149], v[82:83], off
	global_load_dwordx4 v[150:153], v[82:83], off offset:16
	global_load_dwordx4 v[154:157], v[82:83], off offset:32
	global_load_dwordx4 v[158:161], v[82:83], off offset:48
	s_waitcnt vmcnt(4)
; __device__ __forceinline__ unsigned f2bf(float f) { unsigned u = __builtin_bit_cast(unsigned, f); return (u + 0x7fffu + ((u >> 16) & 1u)) >> 16; }
; __device__ __forceinline__ f32x4 mfma16(bf16x8 a, bf16x8 b, f32x4 c) { return __builtin_amdgcn_mfma_f32_16x16x32_bf16(a, b, c, 0, 0, 0); }
; __device__ __forceinline__ void phase0(const Args& a, LAS unsigned char* lds, int tid, int wave, int lane, int vcu, int G, int pmask) {
;     ...
;                     for (int bt = 0; bt < 9; ++bt) {
;                         const int b = 16 * bt + i16; const int k = k0 + 32 * ks + 8 * g;
;                         f32x4 c0 = {0.f, 0.f, 0.f, 0.f}, c1 = c0;
;                         if (b < 129) { const float* cr = b == 0 ? cp + k : cs + (size_t)(b - 1) * DM + k; c0 = *(const f32x4*)cr; c1 = *(const f32x4*)(cr + 4); }
;                         unsigned hb[8], lb[8];
; #pragma unroll
;                         for (int j = 0; j < 8; ++j) { const float c = j < 4 ? c0[j & 3] : c1[j & 3]; const float sv = c * __builtin_amdgcn_rcpf(1.f + __expf(-c)); hb[j] = f2bf(sv); lb[j] = f2bf(sv - __uint_as_float(hb[j] << 16)); }
;                         u32x4 wh, wl; wh.x = hb[0] | (hb[1] << 16); wh.y = hb[2] | (hb[3] << 16); wh.z = hb[4] | (hb[5] << 16); wh.w = hb[6] | (hb[7] << 16);
;                         wl.x = lb[0] | (lb[1] << 16); wl.y = lb[2] | (lb[3] << 16); wl.z = lb[4] | (lb[5] << 16); wl.w = lb[6] | (lb[7] << 16);
;                         const bf16x8 bh = __builtin_bit_cast(bf16x8, wh), bl = __builtin_bit_cast(bf16x8, wl);
; #pragma unroll
;                         for (int nt = 0; nt < 2; ++nt) { acc[nt][bt] = mfma16(ah[nt], bh, acc[nt][bt]); acc[nt][bt] = mfma16(ah[nt], bl, acc[nt][bt]); acc[nt][bt] = mfma16(al[nt], bh, acc[nt][bt]); }
	v_mul_f32_e32 v92, 0xbfb8aa3b, v212
	v_mul_f32_e32 v93, 0xbfb8aa3b, v213
	v_mul_f32_e32 v94, 0xbfb8aa3b, v214
	v_mul_f32_e32 v95, 0xbfb8aa3b, v215
	v_mul_f32_e32 v96, 0xbfb8aa3b, v216
	v_mul_f32_e32 v97, 0xbfb8aa3b, v217
	v_mul_f32_e32 v98, 0xbfb8aa3b, v218
	v_mul_f32_e32 v99, 0xbfb8aa3b, v219
	v_mul_f32_e32 v100, 0xbfb8aa3b, v220
	v_mul_f32_e32 v101, 0xbfb8aa3b, v221
	v_mul_f32_e32 v102, 0xbfb8aa3b, v222
	v_mul_f32_e32 v103, 0xbfb8aa3b, v223
	v_mul_f32_e32 v104, 0xbfb8aa3b, v224
	v_mul_f32_e32 v105, 0xbfb8aa3b, v225
	v_mul_f32_e32 v106, 0xbfb8aa3b, v226
	v_mul_f32_e32 v107, 0xbfb8aa3b, v227
	v_exp_f32_e32 v92, v92
	v_exp_f32_e32 v93, v93
	v_exp_f32_e32 v94, v94
	v_exp_f32_e32 v95, v95
	v_exp_f32_e32 v96, v96
	v_exp_f32_e32 v97, v97
	v_exp_f32_e32 v98, v98
	v_exp_f32_e32 v99, v99
	v_exp_f32_e32 v100, v100
	v_exp_f32_e32 v101, v101
	v_exp_f32_e32 v102, v102
	v_exp_f32_e32 v103, v103
	v_exp_f32_e32 v104, v104
	v_exp_f32_e32 v105, v105
	v_exp_f32_e32 v106, v106
	v_exp_f32_e32 v107, v107
	v_add_f32_e32 v92, 1.0, v92
	v_add_f32_e32 v93, 1.0, v93
	v_add_f32_e32 v94, 1.0, v94
	v_add_f32_e32 v95, 1.0, v95
	v_add_f32_e32 v96, 1.0, v96
	v_add_f32_e32 v97, 1.0, v97
	v_add_f32_e32 v98, 1.0, v98
	v_add_f32_e32 v99, 1.0, v99
	v_add_f32_e32 v100, 1.0, v100
	v_add_f32_e32 v101, 1.0, v101
	v_add_f32_e32 v102, 1.0, v102
	v_add_f32_e32 v103, 1.0, v103
	v_add_f32_e32 v104, 1.0, v104
	v_add_f32_e32 v105, 1.0, v105
	v_add_f32_e32 v106, 1.0, v106
	v_add_f32_e32 v107, 1.0, v107
	v_rcp_f32_e32 v92, v92
	v_rcp_f32_e32 v93, v93
	v_rcp_f32_e32 v94, v94
	v_rcp_f32_e32 v95, v95
	v_rcp_f32_e32 v96, v96
	v_rcp_f32_e32 v97, v97
	v_rcp_f32_e32 v98, v98
	v_rcp_f32_e32 v99, v99
	v_rcp_f32_e32 v100, v100
	v_rcp_f32_e32 v101, v101
	v_rcp_f32_e32 v102, v102
	v_rcp_f32_e32 v103, v103
	v_rcp_f32_e32 v104, v104
	v_rcp_f32_e32 v105, v105
	v_rcp_f32_e32 v106, v106
	v_rcp_f32_e32 v107, v107
	v_mul_f32_e32 v92, v212, v92
	v_mul_f32_e32 v93, v213, v93
	v_mul_f32_e32 v94, v214, v94
	v_mul_f32_e32 v95, v215, v95
	v_mul_f32_e32 v96, v216, v96
	v_mul_f32_e32 v97, v217, v97
	v_mul_f32_e32 v98, v218, v98
	v_mul_f32_e32 v99, v219, v99
	v_mul_f32_e32 v100, v220, v100
	v_mul_f32_e32 v101, v221, v101
	v_mul_f32_e32 v102, v222, v102
	v_mul_f32_e32 v103, v223, v103
	v_mul_f32_e32 v104, v224, v104
	v_mul_f32_e32 v105, v225, v105
	v_mul_f32_e32 v106, v226, v106
	v_mul_f32_e32 v107, v227, v107
	s_nop 1
	v_mfma_f32_16x16x4_f32 v[62:65], v180, v92, v[62:65]
	v_mfma_f32_16x16x4_f32 v[46:49], v196, v92, v[46:49]
	v_mfma_f32_16x16x4_f32 v[62:65], v181, v93, v[62:65]
	v_mfma_f32_16x16x4_f32 v[46:49], v197, v93, v[46:49]
	v_mfma_f32_16x16x4_f32 v[62:65], v182, v94, v[62:65]
	v_mfma_f32_16x16x4_f32 v[46:49], v198, v94, v[46:49]
	v_mfma_f32_16x16x4_f32 v[62:65], v183, v95, v[62:65]
	v_mfma_f32_16x16x4_f32 v[46:49], v199, v95, v[46:49]
	v_mfma_f32_16x16x4_f32 v[62:65], v184, v96, v[62:65]
	v_mfma_f32_16x16x4_f32 v[46:49], v200, v96, v[46:49]
	v_mfma_f32_16x16x4_f32 v[62:65], v185, v97, v[62:65]
	v_mfma_f32_16x16x4_f32 v[46:49], v201, v97, v[46:49]
	v_mfma_f32_16x16x4_f32 v[62:65], v186, v98, v[62:65]
	v_mfma_f32_16x16x4_f32 v[46:49], v202, v98, v[46:49]
	v_mfma_f32_16x16x4_f32 v[62:65], v187, v99, v[62:65]
	v_mfma_f32_16x16x4_f32 v[46:49], v203, v99, v[46:49]
	v_mfma_f32_16x16x4_f32 v[62:65], v188, v100, v[62:65]
	v_mfma_f32_16x16x4_f32 v[46:49], v204, v100, v[46:49]
	v_mfma_f32_16x16x4_f32 v[62:65], v189, v101, v[62:65]
	v_mfma_f32_16x16x4_f32 v[46:49], v205, v101, v[46:49]
	v_mfma_f32_16x16x4_f32 v[62:65], v190, v102, v[62:65]
	v_mfma_f32_16x16x4_f32 v[46:49], v206, v102, v[46:49]
	v_mfma_f32_16x16x4_f32 v[62:65], v191, v103, v[62:65]
	v_mfma_f32_16x16x4_f32 v[46:49], v207, v103, v[46:49]
	v_mfma_f32_16x16x4_f32 v[62:65], v192, v104, v[62:65]
	v_mfma_f32_16x16x4_f32 v[46:49], v208, v104, v[46:49]
	v_mfma_f32_16x16x4_f32 v[62:65], v193, v105, v[62:65]
	v_mfma_f32_16x16x4_f32 v[46:49], v209, v105, v[46:49]
	v_mfma_f32_16x16x4_f32 v[62:65], v194, v106, v[62:65]
	v_mfma_f32_16x16x4_f32 v[46:49], v210, v106, v[46:49]
	v_mfma_f32_16x16x4_f32 v[62:65], v195, v107, v[62:65]
	v_mfma_f32_16x16x4_f32 v[46:49], v211, v107, v[46:49]
	v_lshl_add_u64 v[82:83], v[82:83], 0, s[88:89]
	global_load_dwordx4 v[212:215], v[82:83], off
	global_load_dwordx4 v[216:219], v[82:83], off offset:16
	global_load_dwordx4 v[220:223], v[82:83], off offset:32
	global_load_dwordx4 v[224:227], v[82:83], off offset:48
	s_waitcnt vmcnt(4)
; __device__ __forceinline__ unsigned f2bf(float f) { unsigned u = __builtin_bit_cast(unsigned, f); return (u + 0x7fffu + ((u >> 16) & 1u)) >> 16; }
; __device__ __forceinline__ f32x4 mfma16(bf16x8 a, bf16x8 b, f32x4 c) { return __builtin_amdgcn_mfma_f32_16x16x32_bf16(a, b, c, 0, 0, 0); }
; __device__ __forceinline__ void phase0(const Args& a, LAS unsigned char* lds, int tid, int wave, int lane, int vcu, int G, int pmask) {
;     ...
;                     for (int bt = 0; bt < 9; ++bt) {
;                         const int b = 16 * bt + i16; const int k = k0 + 32 * ks + 8 * g;
;                         f32x4 c0 = {0.f, 0.f, 0.f, 0.f}, c1 = c0;
;                         if (b < 129) { const float* cr = b == 0 ? cp + k : cs + (size_t)(b - 1) * DM + k; c0 = *(const f32x4*)cr; c1 = *(const f32x4*)(cr + 4); }
;                         unsigned hb[8], lb[8];
; #pragma unroll
;                         for (int j = 0; j < 8; ++j) { const float c = j < 4 ? c0[j & 3] : c1[j & 3]; const float sv = c * __builtin_amdgcn_rcpf(1.f + __expf(-c)); hb[j] = f2bf(sv); lb[j] = f2bf(sv - __uint_as_float(hb[j] << 16)); }
;                         u32x4 wh, wl; wh.x = hb[0] | (hb[1] << 16); wh.y = hb[2] | (hb[3] << 16); wh.z = hb[4] | (hb[5] << 16); wh.w = hb[6] | (hb[7] << 16);
;                         wl.x = lb[0] | (lb[1] << 16); wl.y = lb[2] | (lb[3] << 16); wl.z = lb[4] | (lb[5] << 16); wl.w = lb[6] | (lb[7] << 16);
;                         const bf16x8 bh = __builtin_bit_cast(bf16x8, wh), bl = __builtin_bit_cast(bf16x8, wl);
; #pragma unroll
;                         for (int nt = 0; nt < 2; ++nt) { acc[nt][bt] = mfma16(ah[nt], bh, acc[nt][bt]); acc[nt][bt] = mfma16(ah[nt], bl, acc[nt][bt]); acc[nt][bt] = mfma16(al[nt], bh, acc[nt][bt]); }
	v_mul_f32_e32 v92, 0xbfb8aa3b, v146
	v_mul_f32_e32 v93, 0xbfb8aa3b, v147
	v_mul_f32_e32 v94, 0xbfb8aa3b, v148
	v_mul_f32_e32 v95, 0xbfb8aa3b, v149
	v_mul_f32_e32 v96, 0xbfb8aa3b, v150
	v_mul_f32_e32 v97, 0xbfb8aa3b, v151
	v_mul_f32_e32 v98, 0xbfb8aa3b, v152
	v_mul_f32_e32 v99, 0xbfb8aa3b, v153
	v_mul_f32_e32 v100, 0xbfb8aa3b, v154
	v_mul_f32_e32 v101, 0xbfb8aa3b, v155
	v_mul_f32_e32 v102, 0xbfb8aa3b, v156
	v_mul_f32_e32 v103, 0xbfb8aa3b, v157
	v_mul_f32_e32 v104, 0xbfb8aa3b, v158
	v_mul_f32_e32 v105, 0xbfb8aa3b, v159
	v_mul_f32_e32 v106, 0xbfb8aa3b, v160
	v_mul_f32_e32 v107, 0xbfb8aa3b, v161
	v_exp_f32_e32 v92, v92
	v_exp_f32_e32 v93, v93
	v_exp_f32_e32 v94, v94
	v_exp_f32_e32 v95, v95
	v_exp_f32_e32 v96, v96
	v_exp_f32_e32 v97, v97
	v_exp_f32_e32 v98, v98
	v_exp_f32_e32 v99, v99
	v_exp_f32_e32 v100, v100
	v_exp_f32_e32 v101, v101
	v_exp_f32_e32 v102, v102
	v_exp_f32_e32 v103, v103
	v_exp_f32_e32 v104, v104
	v_exp_f32_e32 v105, v105
	v_exp_f32_e32 v106, v106
	v_exp_f32_e32 v107, v107
	v_add_f32_e32 v92, 1.0, v92
	v_add_f32_e32 v93, 1.0, v93
	v_add_f32_e32 v94, 1.0, v94
	v_add_f32_e32 v95, 1.0, v95
	v_add_f32_e32 v96, 1.0, v96
	v_add_f32_e32 v97, 1.0, v97
	v_add_f32_e32 v98, 1.0, v98
	v_add_f32_e32 v99, 1.0, v99
	v_add_f32_e32 v100, 1.0, v100
	v_add_f32_e32 v101, 1.0, v101
	v_add_f32_e32 v102, 1.0, v102
	v_add_f32_e32 v103, 1.0, v103
	v_add_f32_e32 v104, 1.0, v104
	v_add_f32_e32 v105, 1.0, v105
	v_add_f32_e32 v106, 1.0, v106
	v_add_f32_e32 v107, 1.0, v107
	v_rcp_f32_e32 v92, v92
	v_rcp_f32_e32 v93, v93
	v_rcp_f32_e32 v94, v94
	v_rcp_f32_e32 v95, v95
	v_rcp_f32_e32 v96, v96
	v_rcp_f32_e32 v97, v97
	v_rcp_f32_e32 v98, v98
	v_rcp_f32_e32 v99, v99
	v_rcp_f32_e32 v100, v100
	v_rcp_f32_e32 v101, v101
	v_rcp_f32_e32 v102, v102
	v_rcp_f32_e32 v103, v103
	v_rcp_f32_e32 v104, v104
	v_rcp_f32_e32 v105, v105
	v_rcp_f32_e32 v106, v106
	v_rcp_f32_e32 v107, v107
	v_mul_f32_e32 v92, v146, v92
	v_mul_f32_e32 v93, v147, v93
	v_mul_f32_e32 v94, v148, v94
	v_mul_f32_e32 v95, v149, v95
	v_mul_f32_e32 v96, v150, v96
	v_mul_f32_e32 v97, v151, v97
	v_mul_f32_e32 v98, v152, v98
	v_mul_f32_e32 v99, v153, v99
	v_mul_f32_e32 v100, v154, v100
	v_mul_f32_e32 v101, v155, v101
	v_mul_f32_e32 v102, v156, v102
	v_mul_f32_e32 v103, v157, v103
	v_mul_f32_e32 v104, v158, v104
	v_mul_f32_e32 v105, v159, v105
	v_mul_f32_e32 v106, v160, v106
	v_mul_f32_e32 v107, v161, v107
	s_nop 1
	v_mfma_f32_16x16x4_f32 v[58:61], v180, v92, v[58:61]
	v_mfma_f32_16x16x4_f32 v[38:41], v196, v92, v[38:41]
	v_mfma_f32_16x16x4_f32 v[58:61], v181, v93, v[58:61]
	v_mfma_f32_16x16x4_f32 v[38:41], v197, v93, v[38:41]
	v_mfma_f32_16x16x4_f32 v[58:61], v182, v94, v[58:61]
	v_mfma_f32_16x16x4_f32 v[38:41], v198, v94, v[38:41]
	v_mfma_f32_16x16x4_f32 v[58:61], v183, v95, v[58:61]
	v_mfma_f32_16x16x4_f32 v[38:41], v199, v95, v[38:41]
	v_mfma_f32_16x16x4_f32 v[58:61], v184, v96, v[58:61]
	v_mfma_f32_16x16x4_f32 v[38:41], v200, v96, v[38:41]
	v_mfma_f32_16x16x4_f32 v[58:61], v185, v97, v[58:61]
	v_mfma_f32_16x16x4_f32 v[38:41], v201, v97, v[38:41]
	v_mfma_f32_16x16x4_f32 v[58:61], v186, v98, v[58:61]
	v_mfma_f32_16x16x4_f32 v[38:41], v202, v98, v[38:41]
	v_mfma_f32_16x16x4_f32 v[58:61], v187, v99, v[58:61]
	v_mfma_f32_16x16x4_f32 v[38:41], v203, v99, v[38:41]
	v_mfma_f32_16x16x4_f32 v[58:61], v188, v100, v[58:61]
	v_mfma_f32_16x16x4_f32 v[38:41], v204, v100, v[38:41]
	v_mfma_f32_16x16x4_f32 v[58:61], v189, v101, v[58:61]
	v_mfma_f32_16x16x4_f32 v[38:41], v205, v101, v[38:41]
	v_mfma_f32_16x16x4_f32 v[58:61], v190, v102, v[58:61]
	v_mfma_f32_16x16x4_f32 v[38:41], v206, v102, v[38:41]
	v_mfma_f32_16x16x4_f32 v[58:61], v191, v103, v[58:61]
	v_mfma_f32_16x16x4_f32 v[38:41], v207, v103, v[38:41]
	v_mfma_f32_16x16x4_f32 v[58:61], v192, v104, v[58:61]
	v_mfma_f32_16x16x4_f32 v[38:41], v208, v104, v[38:41]
	v_mfma_f32_16x16x4_f32 v[58:61], v193, v105, v[58:61]
	v_mfma_f32_16x16x4_f32 v[38:41], v209, v105, v[38:41]
	v_mfma_f32_16x16x4_f32 v[58:61], v194, v106, v[58:61]
	v_mfma_f32_16x16x4_f32 v[38:41], v210, v106, v[38:41]
	v_mfma_f32_16x16x4_f32 v[58:61], v195, v107, v[58:61]
	v_mfma_f32_16x16x4_f32 v[38:41], v211, v107, v[38:41]
	global_load_dwordx4 v[146:149], v[88:89], off
	global_load_dwordx4 v[150:153], v[88:89], off offset:16
	global_load_dwordx4 v[154:157], v[88:89], off offset:32
	global_load_dwordx4 v[158:161], v[88:89], off offset:48
	s_waitcnt vmcnt(4)
; __device__ __forceinline__ unsigned f2bf(float f) { unsigned u = __builtin_bit_cast(unsigned, f); return (u + 0x7fffu + ((u >> 16) & 1u)) >> 16; }
; __device__ __forceinline__ f32x4 mfma16(bf16x8 a, bf16x8 b, f32x4 c) { return __builtin_amdgcn_mfma_f32_16x16x32_bf16(a, b, c, 0, 0, 0); }
; __device__ __forceinline__ void phase0(const Args& a, LAS unsigned char* lds, int tid, int wave, int lane, int vcu, int G, int pmask) {
;     ...
;                     for (int bt = 0; bt < 9; ++bt) {
;                         const int b = 16 * bt + i16; const int k = k0 + 32 * ks + 8 * g;
;                         f32x4 c0 = {0.f, 0.f, 0.f, 0.f}, c1 = c0;
;                         if (b < 129) { const float* cr = b == 0 ? cp + k : cs + (size_t)(b - 1) * DM + k; c0 = *(const f32x4*)cr; c1 = *(const f32x4*)(cr + 4); }
;                         unsigned hb[8], lb[8];
; #pragma unroll
;                         for (int j = 0; j < 8; ++j) { const float c = j < 4 ? c0[j & 3] : c1[j & 3]; const float sv = c * __builtin_amdgcn_rcpf(1.f + __expf(-c)); hb[j] = f2bf(sv); lb[j] = f2bf(sv - __uint_as_float(hb[j] << 16)); }
;                         u32x4 wh, wl; wh.x = hb[0] | (hb[1] << 16); wh.y = hb[2] | (hb[3] << 16); wh.z = hb[4] | (hb[5] << 16); wh.w = hb[6] | (hb[7] << 16);
;                         wl.x = lb[0] | (lb[1] << 16); wl.y = lb[2] | (lb[3] << 16); wl.z = lb[4] | (lb[5] << 16); wl.w = lb[6] | (lb[7] << 16);
;                         const bf16x8 bh = __builtin_bit_cast(bf16x8, wh), bl = __builtin_bit_cast(bf16x8, wl);
; #pragma unroll
;                         for (int nt = 0; nt < 2; ++nt) { acc[nt][bt] = mfma16(ah[nt], bh, acc[nt][bt]); acc[nt][bt] = mfma16(ah[nt], bl, acc[nt][bt]); acc[nt][bt] = mfma16(al[nt], bh, acc[nt][bt]); }
	v_mul_f32_e32 v92, 0xbfb8aa3b, v212
	v_mul_f32_e32 v93, 0xbfb8aa3b, v213
	v_mul_f32_e32 v94, 0xbfb8aa3b, v214
	v_mul_f32_e32 v95, 0xbfb8aa3b, v215
	v_mul_f32_e32 v96, 0xbfb8aa3b, v216
	v_mul_f32_e32 v97, 0xbfb8aa3b, v217
	v_mul_f32_e32 v98, 0xbfb8aa3b, v218
	v_mul_f32_e32 v99, 0xbfb8aa3b, v219
	v_mul_f32_e32 v100, 0xbfb8aa3b, v220
	v_mul_f32_e32 v101, 0xbfb8aa3b, v221
	v_mul_f32_e32 v102, 0xbfb8aa3b, v222
	v_mul_f32_e32 v103, 0xbfb8aa3b, v223
	v_mul_f32_e32 v104, 0xbfb8aa3b, v224
	v_mul_f32_e32 v105, 0xbfb8aa3b, v225
	v_mul_f32_e32 v106, 0xbfb8aa3b, v226
	v_mul_f32_e32 v107, 0xbfb8aa3b, v227
	v_exp_f32_e32 v92, v92
	v_exp_f32_e32 v93, v93
	v_exp_f32_e32 v94, v94
	v_exp_f32_e32 v95, v95
	v_exp_f32_e32 v96, v96
	v_exp_f32_e32 v97, v97
	v_exp_f32_e32 v98, v98
	v_exp_f32_e32 v99, v99
	v_exp_f32_e32 v100, v100
	v_exp_f32_e32 v101, v101
	v_exp_f32_e32 v102, v102
	v_exp_f32_e32 v103, v103
	v_exp_f32_e32 v104, v104
	v_exp_f32_e32 v105, v105
	v_exp_f32_e32 v106, v106
	v_exp_f32_e32 v107, v107
	v_add_f32_e32 v92, 1.0, v92
	v_add_f32_e32 v93, 1.0, v93
	v_add_f32_e32 v94, 1.0, v94
	v_add_f32_e32 v95, 1.0, v95
	v_add_f32_e32 v96, 1.0, v96
	v_add_f32_e32 v97, 1.0, v97
	v_add_f32_e32 v98, 1.0, v98
	v_add_f32_e32 v99, 1.0, v99
	v_add_f32_e32 v100, 1.0, v100
	v_add_f32_e32 v101, 1.0, v101
	v_add_f32_e32 v102, 1.0, v102
	v_add_f32_e32 v103, 1.0, v103
	v_add_f32_e32 v104, 1.0, v104
	v_add_f32_e32 v105, 1.0, v105
	v_add_f32_e32 v106, 1.0, v106
	v_add_f32_e32 v107, 1.0, v107
	v_rcp_f32_e32 v92, v92
	v_rcp_f32_e32 v93, v93
	v_rcp_f32_e32 v94, v94
	v_rcp_f32_e32 v95, v95
	v_rcp_f32_e32 v96, v96
	v_rcp_f32_e32 v97, v97
	v_rcp_f32_e32 v98, v98
	v_rcp_f32_e32 v99, v99
	v_rcp_f32_e32 v100, v100
	v_rcp_f32_e32 v101, v101
	v_rcp_f32_e32 v102, v102
	v_rcp_f32_e32 v103, v103
	v_rcp_f32_e32 v104, v104
	v_rcp_f32_e32 v105, v105
	v_rcp_f32_e32 v106, v106
	v_rcp_f32_e32 v107, v107
	v_mul_f32_e32 v92, v212, v92
	v_mul_f32_e32 v93, v213, v93
	v_mul_f32_e32 v94, v214, v94
	v_mul_f32_e32 v95, v215, v95
	v_mul_f32_e32 v96, v216, v96
	v_mul_f32_e32 v97, v217, v97
	v_mul_f32_e32 v98, v218, v98
	v_mul_f32_e32 v99, v219, v99
	v_mul_f32_e32 v100, v220, v100
	v_mul_f32_e32 v101, v221, v101
	v_mul_f32_e32 v102, v222, v102
	v_mul_f32_e32 v103, v223, v103
	v_mul_f32_e32 v104, v224, v104
	v_mul_f32_e32 v105, v225, v105
	v_mul_f32_e32 v106, v226, v106
	v_mul_f32_e32 v107, v227, v107
	s_nop 1
	v_mfma_f32_16x16x4_f32 v[26:29], v180, v92, v[26:29]
	v_mfma_f32_16x16x4_f32 v[14:17], v196, v92, v[14:17]
	v_mfma_f32_16x16x4_f32 v[26:29], v181, v93, v[26:29]
	v_mfma_f32_16x16x4_f32 v[14:17], v197, v93, v[14:17]
	v_mfma_f32_16x16x4_f32 v[26:29], v182, v94, v[26:29]
	v_mfma_f32_16x16x4_f32 v[14:17], v198, v94, v[14:17]
	v_mfma_f32_16x16x4_f32 v[26:29], v183, v95, v[26:29]
	v_mfma_f32_16x16x4_f32 v[14:17], v199, v95, v[14:17]
	v_mfma_f32_16x16x4_f32 v[26:29], v184, v96, v[26:29]
	v_mfma_f32_16x16x4_f32 v[14:17], v200, v96, v[14:17]
	v_mfma_f32_16x16x4_f32 v[26:29], v185, v97, v[26:29]
	v_mfma_f32_16x16x4_f32 v[14:17], v201, v97, v[14:17]
	v_mfma_f32_16x16x4_f32 v[26:29], v186, v98, v[26:29]
	v_mfma_f32_16x16x4_f32 v[14:17], v202, v98, v[14:17]
	v_mfma_f32_16x16x4_f32 v[26:29], v187, v99, v[26:29]
	v_mfma_f32_16x16x4_f32 v[14:17], v203, v99, v[14:17]
	v_mfma_f32_16x16x4_f32 v[26:29], v188, v100, v[26:29]
	v_mfma_f32_16x16x4_f32 v[14:17], v204, v100, v[14:17]
	v_mfma_f32_16x16x4_f32 v[26:29], v189, v101, v[26:29]
	v_mfma_f32_16x16x4_f32 v[14:17], v205, v101, v[14:17]
	v_mfma_f32_16x16x4_f32 v[26:29], v190, v102, v[26:29]
	v_mfma_f32_16x16x4_f32 v[14:17], v206, v102, v[14:17]
	v_mfma_f32_16x16x4_f32 v[26:29], v191, v103, v[26:29]
	v_mfma_f32_16x16x4_f32 v[14:17], v207, v103, v[14:17]
	v_mfma_f32_16x16x4_f32 v[26:29], v192, v104, v[26:29]
	v_mfma_f32_16x16x4_f32 v[14:17], v208, v104, v[14:17]
	v_mfma_f32_16x16x4_f32 v[26:29], v193, v105, v[26:29]
	v_mfma_f32_16x16x4_f32 v[14:17], v209, v105, v[14:17]
	v_mfma_f32_16x16x4_f32 v[26:29], v194, v106, v[26:29]
	v_mfma_f32_16x16x4_f32 v[14:17], v210, v106, v[14:17]
	v_mfma_f32_16x16x4_f32 v[26:29], v195, v107, v[26:29]
	v_mfma_f32_16x16x4_f32 v[14:17], v211, v107, v[14:17]
	s_waitcnt vmcnt(0)
; __device__ __forceinline__ unsigned f2bf(float f) { unsigned u = __builtin_bit_cast(unsigned, f); return (u + 0x7fffu + ((u >> 16) & 1u)) >> 16; }
; __device__ __forceinline__ f32x4 mfma16(bf16x8 a, bf16x8 b, f32x4 c) { return __builtin_amdgcn_mfma_f32_16x16x32_bf16(a, b, c, 0, 0, 0); }
; #define LDS_WAIT() asm volatile("s_waitcnt lgkmcnt(0)" ::: "memory")
; __device__ __forceinline__ void phase0(const Args& a, LAS unsigned char* lds, int tid, int wave, int lane, int vcu, int G, int pmask) {
;     ...
;                     for (int bt = 0; bt < 9; ++bt) {
;                         const int b = 16 * bt + i16; const int k = k0 + 32 * ks + 8 * g;
;                         f32x4 c0 = {0.f, 0.f, 0.f, 0.f}, c1 = c0;
;                         if (b < 129) { const float* cr = b == 0 ? cp + k : cs + (size_t)(b - 1) * DM + k; c0 = *(const f32x4*)cr; c1 = *(const f32x4*)(cr + 4); }
;                         unsigned hb[8], lb[8];
; #pragma unroll
;                         for (int j = 0; j < 8; ++j) { const float c = j < 4 ? c0[j & 3] : c1[j & 3]; const float sv = c * __builtin_amdgcn_rcpf(1.f + __expf(-c)); hb[j] = f2bf(sv); lb[j] = f2bf(sv - __uint_as_float(hb[j] << 16)); }
;                         u32x4 wh, wl; wh.x = hb[0] | (hb[1] << 16); wh.y = hb[2] | (hb[3] << 16); wh.z = hb[4] | (hb[5] << 16); wh.w = hb[6] | (hb[7] << 16);
;                         wl.x = lb[0] | (lb[1] << 16); wl.y = lb[2] | (lb[3] << 16); wl.z = lb[4] | (lb[5] << 16); wl.w = lb[6] | (lb[7] << 16);
;                         const bf16x8 bh = __builtin_bit_cast(bf16x8, wh), bl = __builtin_bit_cast(bf16x8, wl);
; #pragma unroll
;                         for (int nt = 0; nt < 2; ++nt) { acc[nt][bt] = mfma16(ah[nt], bh, acc[nt][bt]); acc[nt][bt] = mfma16(ah[nt], bl, acc[nt][bt]); acc[nt][bt] = mfma16(al[nt], bh, acc[nt][bt]); }
;                     }
;                 }
;                 LDS_WAIT(); asm volatile("" ::: "memory");
	v_mul_f32_e32 v92, 0xbfb8aa3b, v146
	v_mul_f32_e32 v93, 0xbfb8aa3b, v147
	v_mul_f32_e32 v94, 0xbfb8aa3b, v148
	v_mul_f32_e32 v95, 0xbfb8aa3b, v149
	v_mul_f32_e32 v96, 0xbfb8aa3b, v150
	v_mul_f32_e32 v97, 0xbfb8aa3b, v151
	v_mul_f32_e32 v98, 0xbfb8aa3b, v152
	v_mul_f32_e32 v99, 0xbfb8aa3b, v153
	v_mul_f32_e32 v100, 0xbfb8aa3b, v154
	v_mul_f32_e32 v101, 0xbfb8aa3b, v155
	v_mul_f32_e32 v102, 0xbfb8aa3b, v156
	v_mul_f32_e32 v103, 0xbfb8aa3b, v157
	v_mul_f32_e32 v104, 0xbfb8aa3b, v158
	v_mul_f32_e32 v105, 0xbfb8aa3b, v159
	v_mul_f32_e32 v106, 0xbfb8aa3b, v160
	v_mul_f32_e32 v107, 0xbfb8aa3b, v161
	v_exp_f32_e32 v92, v92
	v_exp_f32_e32 v93, v93
	v_exp_f32_e32 v94, v94
	v_exp_f32_e32 v95, v95
	v_exp_f32_e32 v96, v96
	v_exp_f32_e32 v97, v97
	v_exp_f32_e32 v98, v98
	v_exp_f32_e32 v99, v99
	v_exp_f32_e32 v100, v100
	v_exp_f32_e32 v101, v101
	v_exp_f32_e32 v102, v102
	v_exp_f32_e32 v103, v103
	v_exp_f32_e32 v104, v104
	v_exp_f32_e32 v105, v105
	v_exp_f32_e32 v106, v106
	v_exp_f32_e32 v107, v107
	v_add_f32_e32 v92, 1.0, v92
	v_add_f32_e32 v93, 1.0, v93
	v_add_f32_e32 v94, 1.0, v94
	v_add_f32_e32 v95, 1.0, v95
	v_add_f32_e32 v96, 1.0, v96
	v_add_f32_e32 v97, 1.0, v97
	v_add_f32_e32 v98, 1.0, v98
	v_add_f32_e32 v99, 1.0, v99
	v_add_f32_e32 v100, 1.0, v100
	v_add_f32_e32 v101, 1.0, v101
	v_add_f32_e32 v102, 1.0, v102
	v_add_f32_e32 v103, 1.0, v103
	v_add_f32_e32 v104, 1.0, v104
	v_add_f32_e32 v105, 1.0, v105
	v_add_f32_e32 v106, 1.0, v106
	v_add_f32_e32 v107, 1.0, v107
	v_rcp_f32_e32 v92, v92
	v_rcp_f32_e32 v93, v93
	v_rcp_f32_e32 v94, v94
	v_rcp_f32_e32 v95, v95
	v_rcp_f32_e32 v96, v96
	v_rcp_f32_e32 v97, v97
	v_rcp_f32_e32 v98, v98
	v_rcp_f32_e32 v99, v99
	v_rcp_f32_e32 v100, v100
	v_rcp_f32_e32 v101, v101
	v_rcp_f32_e32 v102, v102
	v_rcp_f32_e32 v103, v103
	v_rcp_f32_e32 v104, v104
	v_rcp_f32_e32 v105, v105
	v_rcp_f32_e32 v106, v106
	v_rcp_f32_e32 v107, v107
	v_mul_f32_e32 v92, v146, v92
	v_mul_f32_e32 v93, v147, v93
	v_mul_f32_e32 v94, v148, v94
	v_mul_f32_e32 v95, v149, v95
	v_mul_f32_e32 v96, v150, v96
	v_mul_f32_e32 v97, v151, v97
	v_mul_f32_e32 v98, v152, v98
	v_mul_f32_e32 v99, v153, v99
	v_mul_f32_e32 v100, v154, v100
	v_mul_f32_e32 v101, v155, v101
	v_mul_f32_e32 v102, v156, v102
	v_mul_f32_e32 v103, v157, v103
	v_mul_f32_e32 v104, v158, v104
	v_mul_f32_e32 v105, v159, v105
	v_mul_f32_e32 v106, v160, v106
	v_mul_f32_e32 v107, v161, v107
	v_cndmask_b32_e32 v92, 0, v92, vcc
	v_cndmask_b32_e32 v93, 0, v93, vcc
	v_cndmask_b32_e32 v94, 0, v94, vcc
	v_cndmask_b32_e32 v95, 0, v95, vcc
	v_cndmask_b32_e32 v96, 0, v96, vcc
	v_cndmask_b32_e32 v97, 0, v97, vcc
	v_cndmask_b32_e32 v98, 0, v98, vcc
	v_cndmask_b32_e32 v99, 0, v99, vcc
	v_cndmask_b32_e32 v100, 0, v100, vcc
	v_cndmask_b32_e32 v101, 0, v101, vcc
	v_cndmask_b32_e32 v102, 0, v102, vcc
	v_cndmask_b32_e32 v103, 0, v103, vcc
	v_cndmask_b32_e32 v104, 0, v104, vcc
	v_cndmask_b32_e32 v105, 0, v105, vcc
	v_cndmask_b32_e32 v106, 0, v106, vcc
	v_cndmask_b32_e32 v107, 0, v107, vcc
	s_nop 1
	v_mfma_f32_16x16x4_f32 v[22:25], v180, v92, v[22:25]
	v_mfma_f32_16x16x4_f32 v[10:13], v196, v92, v[10:13]
	v_mfma_f32_16x16x4_f32 v[22:25], v181, v93, v[22:25]
	v_mfma_f32_16x16x4_f32 v[10:13], v197, v93, v[10:13]
	v_mfma_f32_16x16x4_f32 v[22:25], v182, v94, v[22:25]
	v_mfma_f32_16x16x4_f32 v[10:13], v198, v94, v[10:13]
	v_mfma_f32_16x16x4_f32 v[22:25], v183, v95, v[22:25]
	v_mfma_f32_16x16x4_f32 v[10:13], v199, v95, v[10:13]
	v_mfma_f32_16x16x4_f32 v[22:25], v184, v96, v[22:25]
	v_mfma_f32_16x16x4_f32 v[10:13], v200, v96, v[10:13]
	v_mfma_f32_16x16x4_f32 v[22:25], v185, v97, v[22:25]
	v_mfma_f32_16x16x4_f32 v[10:13], v201, v97, v[10:13]
	v_mfma_f32_16x16x4_f32 v[22:25], v186, v98, v[22:25]
	v_mfma_f32_16x16x4_f32 v[10:13], v202, v98, v[10:13]
	v_mfma_f32_16x16x4_f32 v[22:25], v187, v99, v[22:25]
	v_mfma_f32_16x16x4_f32 v[10:13], v203, v99, v[10:13]
	v_mfma_f32_16x16x4_f32 v[22:25], v188, v100, v[22:25]
	v_mfma_f32_16x16x4_f32 v[10:13], v204, v100, v[10:13]
	v_mfma_f32_16x16x4_f32 v[22:25], v189, v101, v[22:25]
	v_mfma_f32_16x16x4_f32 v[10:13], v205, v101, v[10:13]
	v_mfma_f32_16x16x4_f32 v[22:25], v190, v102, v[22:25]
	v_mfma_f32_16x16x4_f32 v[10:13], v206, v102, v[10:13]
	v_mfma_f32_16x16x4_f32 v[22:25], v191, v103, v[22:25]
	v_mfma_f32_16x16x4_f32 v[10:13], v207, v103, v[10:13]
	v_mfma_f32_16x16x4_f32 v[22:25], v192, v104, v[22:25]
	v_mfma_f32_16x16x4_f32 v[10:13], v208, v104, v[10:13]
	v_mfma_f32_16x16x4_f32 v[22:25], v193, v105, v[22:25]
	v_mfma_f32_16x16x4_f32 v[10:13], v209, v105, v[10:13]
	v_mfma_f32_16x16x4_f32 v[22:25], v194, v106, v[22:25]
	v_mfma_f32_16x16x4_f32 v[10:13], v210, v106, v[10:13]
	v_mfma_f32_16x16x4_f32 v[22:25], v195, v107, v[22:25]
	v_mfma_f32_16x16x4_f32 v[10:13], v211, v107, v[10:13]
	s_mov_b32 s82, 64
	s_mov_b64 s[56:57], 0
	s_and_b64 vcc, exec, s[54:55]
	s_cbranch_vccnz .LBB0_20
	s_branch .LBB0_14
